# A/B: mid-segment s_setprio 0/1 flips removed from the four K-loops (on v077)
# speedup vs baseline: 1.0037x; 1.0001x over previous
; #define PG8_STAGE(bufoff, gbase, voff) do { _Pragma("unroll") for (int _i = 0; _i < 2; ++_i) \
;         __builtin_amdgcn_global_load_lds((const unsigned*)((const char*)(gbase) + (voff)[_i]), (PG8_LAS unsigned*)(lds + (bufoff) + ldsw + _i * 8192), 16, 0, 0); } while (0)
; #define PG8_LDA(dst, b, h) do { _Pragma("unroll") for (int m = 0; m < 4; ++m) _Pragma("unroll") for (int k = 0; k < 2; ++k) dst[m][k] = *(const PG8_LAS bf16x8*)(lds + PG8_SA(b, h) + aoff + m * 2048 + k * 1024); } while (0)
; #define PG8_LDB(dst, b, h) do { _Pragma("unroll") for (int n = 0; n < 2; ++n) _Pragma("unroll") for (int k = 0; k < 2; ++k) dst[n][k] = *(const PG8_LAS bf16x8*)(lds + PG8_SB(b, h) + boff + n * 2048 + k * 1024); } while (0)
; #define PG8_MMA(ai, bj, At, Bt) do { __builtin_amdgcn_s_setprio(1); _Pragma("unroll") for (int m = 0; m < 4; ++m) _Pragma("unroll") for (int n = 0; n < 2; ++n) _Pragma("unroll") for (int k = 0; k < 2; ++k) \
;         acc[ai][bj][m][n] = __builtin_amdgcn_mfma_f32_16x16x32_bf16(Bt[n][k], At[m][k], acc[ai][bj][m][n], 0, 0, 0); __builtin_amdgcn_s_setprio(0); } while (0)
; #define PG8_WAIT_V(n) asm volatile("s_waitcnt vmcnt(" #n ")" ::: "memory")
; #define PG8_WAIT_L(n) asm volatile("s_waitcnt lgkmcnt(" #n ")" ::: "memory")
; template <class Epi, class Sched, bool ALIGN_EPI = false, bool SP2 = false>
; __device__ __forceinline__ void gemm_phase(PG8_LAS unsigned char* lds, const Gemm g, const Sched& S, const Epi& E, const int wave_) {
;     ...
;             const bool last = (t == nt - 2);
;             const char* a1 = cA + (size_t)(t + 1) * kstep;
;             const char* a2 = last ? nA : cA + (size_t)(t + 2) * kstep; const char* b2 = last ? nB : cB + (size_t)(t + 2) * kstep;
;             const char* a3 = a2 + kstep; const char* b3 = b2 + kstep;
;             if (last && has_next) S.a_ready(nxt);
;             if constexpr (SP2) {
;             PG8_LDB(B0, 0, 0); PG8_LDB(B1, 0, 1); PG8_SCHED; PG8_LDA(At, 0, 0); PG8_STAGE(PG8_SA(1, 1), a1 + hstep, voffA);
;             PG8_WAIT_V(8); PG8_WAIT_L(0); PG8_BAR; PG8_MMA(0, 0, At, B0); PG8_MMA(0, 1, At, B1); PG8_BAR; PG8_SCHED;
;             PG8_LDA(At, 0, 1); PG8_STAGE(PG8_SB(0, 0), b2, voffB); PG8_STAGE(PG8_SB(0, 1), b2 + hstep, voffB); PG8_STAGE(PG8_SA(0, 0), a2, voffA);
;             PG8_WAIT_V(8); PG8_WAIT_L(0); PG8_BAR; PG8_MMA(1, 0, At, B0); PG8_MMA(1, 1, At, B1); PG8_BAR; PG8_SCHED;
.LBB0_129:
	s_waitcnt lgkmcnt(0)
	ds_read_b128 v[158:161], v202
	ds_read_b128 v[162:165], v202 offset:1024
	ds_read_b128 v[166:169], v202 offset:2048
	ds_read_b128 v[170:173], v202 offset:3072
	ds_read_b128 v[174:177], v205
	ds_read_b128 v[178:181], v205 offset:1024
	ds_read_b128 v[182:185], v205 offset:2048
	ds_read_b128 v[186:189], v205 offset:3072
	s_add_u32 s23, s46, 0xfff80080
	s_addc_u32 s24, s47, -1
	s_cmp_eq_u32 s22, 28
	s_cselect_b32 s51, s19, s24
	s_cselect_b32 s50, s39, s23
	s_cselect_b32 s49, s37, s97
	s_cselect_b32 s48, vcc_lo, vcc_hi
	v_lshl_add_u64 v[238:239], s[46:47], 0, v[148:149]
	s_add_i32 m0, s53, 0xc000
	ds_read_b128 v[206:209], v203
	ds_read_b128 v[210:213], v203 offset:1024
	ds_read_b128 v[214:217], v203 offset:2048
	ds_read_b128 v[218:221], v203 offset:3072
	ds_read_b128 v[222:225], v203 offset:4096
	ds_read_b128 v[226:229], v203 offset:5120
	ds_read_b128 v[230:233], v203 offset:6144
	ds_read_b128 v[234:237], v203 offset:7168
	global_load_lds_dwordx4 v[238:239], off
	v_lshl_add_u64 v[238:239], s[46:47], 0, v[150:151]
	s_add_i32 m0, s53, 0xe000
	s_nop 0
	global_load_lds_dwordx4 v[238:239], off
	s_waitcnt vmcnt(8)
	s_waitcnt lgkmcnt(0)
	s_barrier
	s_setprio 1
	s_waitcnt lgkmcnt(0)
	v_mfma_f32_16x16x32_bf16 v[124:127], v[158:161], v[206:209], v[124:127]
	v_mfma_f32_16x16x32_bf16 v[116:119], v[166:169], v[206:209], v[116:119]
	v_mfma_f32_16x16x32_bf16 v[108:111], v[158:161], v[214:217], v[108:111]
	v_mfma_f32_16x16x32_bf16 v[100:103], v[166:169], v[214:217], v[100:103]
	v_mfma_f32_16x16x32_bf16 v[92:95], v[158:161], v[222:225], v[92:95]
	v_mfma_f32_16x16x32_bf16 v[84:87], v[166:169], v[222:225], v[84:87]
	v_mfma_f32_16x16x32_bf16 v[76:79], v[158:161], v[230:233], v[76:79]
	v_mfma_f32_16x16x32_bf16 v[68:71], v[166:169], v[230:233], v[68:71]
	v_mfma_f32_16x16x32_bf16 v[124:127], v[162:165], v[210:213], v[124:127]
	v_mfma_f32_16x16x32_bf16 v[116:119], v[170:173], v[210:213], v[116:119]
	v_mfma_f32_16x16x32_bf16 v[108:111], v[162:165], v[218:221], v[108:111]
	v_mfma_f32_16x16x32_bf16 v[100:103], v[170:173], v[218:221], v[100:103]
	v_mfma_f32_16x16x32_bf16 v[92:95], v[162:165], v[226:229], v[92:95]
	v_mfma_f32_16x16x32_bf16 v[84:87], v[170:173], v[226:229], v[84:87]
	v_mfma_f32_16x16x32_bf16 v[76:79], v[162:165], v[234:237], v[76:79]
	v_mfma_f32_16x16x32_bf16 v[68:71], v[170:173], v[234:237], v[68:71]
	v_mfma_f32_16x16x32_bf16 v[120:123], v[174:177], v[206:209], v[120:123]
	v_mfma_f32_16x16x32_bf16 v[112:115], v[182:185], v[206:209], v[112:115]
	v_mfma_f32_16x16x32_bf16 v[104:107], v[174:177], v[214:217], v[104:107]
	v_mfma_f32_16x16x32_bf16 v[96:99], v[182:185], v[214:217], v[96:99]
	v_mfma_f32_16x16x32_bf16 v[88:91], v[174:177], v[222:225], v[88:91]
	v_mfma_f32_16x16x32_bf16 v[80:83], v[182:185], v[222:225], v[80:83]
	v_mfma_f32_16x16x32_bf16 v[72:75], v[174:177], v[230:233], v[72:75]
	v_mfma_f32_16x16x32_bf16 v[64:67], v[182:185], v[230:233], v[64:67]
	v_mfma_f32_16x16x32_bf16 v[120:123], v[178:181], v[210:213], v[120:123]
	v_mfma_f32_16x16x32_bf16 v[112:115], v[186:189], v[210:213], v[112:115]
	v_mfma_f32_16x16x32_bf16 v[104:107], v[178:181], v[218:221], v[104:107]
	v_mfma_f32_16x16x32_bf16 v[96:99], v[186:189], v[218:221], v[96:99]
	v_mfma_f32_16x16x32_bf16 v[88:91], v[178:181], v[226:229], v[88:91]
	v_mfma_f32_16x16x32_bf16 v[80:83], v[186:189], v[226:229], v[80:83]
	v_mfma_f32_16x16x32_bf16 v[72:75], v[178:181], v[234:237], v[72:75]
	v_mfma_f32_16x16x32_bf16 v[64:67], v[186:189], v[234:237], v[64:67]
	s_setprio 0
	s_barrier
	s_add_i32 s23, s67, s52
	v_lshl_add_u64 v[238:239], s[48:49], 0, v[130:131]
	s_mov_b32 m0, s23
	ds_read_b128 v[206:209], v203 offset:16384
	ds_read_b128 v[210:213], v203 offset:17408
	ds_read_b128 v[214:217], v203 offset:18432
	ds_read_b128 v[218:221], v203 offset:19456
	ds_read_b128 v[222:225], v203 offset:20480
	ds_read_b128 v[226:229], v203 offset:21504
	ds_read_b128 v[230:233], v203 offset:22528
	ds_read_b128 v[234:237], v203 offset:23552
	global_load_lds_dwordx4 v[238:239], off
	s_add_i32 m0, s23, 0x2000
	s_add_u32 s24, s48, 0x80000
	v_lshl_add_u64 v[240:241], s[48:49], 0, v[134:135]
	s_addc_u32 s25, s49, 0
	s_add_i32 s23, s71, s52
	global_load_lds_dwordx4 v[240:241], off
	v_lshl_add_u64 v[242:243], s[24:25], 0, v[130:131]
	s_mov_b32 m0, s23
	v_lshl_add_u64 v[244:245], s[50:51], 0, v[132:133]
	global_load_lds_dwordx4 v[242:243], off
	v_lshl_add_u64 v[242:243], s[24:25], 0, v[134:135]
	s_add_i32 m0, s23, 0x2000
	s_nop 0
	global_load_lds_dwordx4 v[242:243], off
	v_lshl_add_u64 v[242:243], s[50:51], 0, v[128:129]
	s_mov_b32 m0, s53
	s_nop 0
	global_load_lds_dwordx4 v[242:243], off
	s_mov_b32 m0, s54
	s_nop 0
	global_load_lds_dwordx4 v[244:245], off
	s_waitcnt vmcnt(8)
	s_waitcnt lgkmcnt(0)
	s_barrier
; #define PG8_STAGE(bufoff, gbase, voff) do { _Pragma("unroll") for (int _i = 0; _i < 2; ++_i) \
;         __builtin_amdgcn_global_load_lds((const unsigned*)((const char*)(gbase) + (voff)[_i]), (PG8_LAS unsigned*)(lds + (bufoff) + ldsw + _i * 8192), 16, 0, 0); } while (0)
; #define PG8_LDA(dst, b, h) do { _Pragma("unroll") for (int m = 0; m < 4; ++m) _Pragma("unroll") for (int k = 0; k < 2; ++k) dst[m][k] = *(const PG8_LAS bf16x8*)(lds + PG8_SA(b, h) + aoff + m * 2048 + k * 1024); } while (0)
; #define PG8_LDB(dst, b, h) do { _Pragma("unroll") for (int n = 0; n < 2; ++n) _Pragma("unroll") for (int k = 0; k < 2; ++k) dst[n][k] = *(const PG8_LAS bf16x8*)(lds + PG8_SB(b, h) + boff + n * 2048 + k * 1024); } while (0)
; #define PG8_MMA(ai, bj, At, Bt) do { __builtin_amdgcn_s_setprio(1); _Pragma("unroll") for (int m = 0; m < 4; ++m) _Pragma("unroll") for (int n = 0; n < 2; ++n) _Pragma("unroll") for (int k = 0; k < 2; ++k) \
;         acc[ai][bj][m][n] = __builtin_amdgcn_mfma_f32_16x16x32_bf16(Bt[n][k], At[m][k], acc[ai][bj][m][n], 0, 0, 0); __builtin_amdgcn_s_setprio(0); } while (0)
; #define PG8_WAIT_V(n) asm volatile("s_waitcnt vmcnt(" #n ")" ::: "memory")
; #define PG8_WAIT_L(n) asm volatile("s_waitcnt lgkmcnt(" #n ")" ::: "memory")
; #define PG8_BAR __builtin_amdgcn_s_barrier()
; #define PG8_SCHED __builtin_amdgcn_sched_barrier(0)
; template <class Epi, class Sched, bool ALIGN_EPI = false, bool SP2 = false>
; __device__ __forceinline__ void gemm_phase(PG8_LAS unsigned char* lds, const Gemm g, const Sched& S, const Epi& E, const int wave_) {
;     ...
;             PG8_WAIT_V(8); PG8_WAIT_L(0); PG8_BAR; PG8_MMA(1, 0, At, B0); PG8_MMA(1, 1, At, B1); PG8_BAR; PG8_SCHED;
;             PG8_LDB(B0, 1, 0); PG8_LDB(B1, 1, 1); PG8_SCHED; PG8_LDA(At, 1, 0); PG8_STAGE(PG8_SA(0, 1), a2 + hstep, voffA);
;             PG8_WAIT_V(8); PG8_WAIT_L(0); PG8_BAR; PG8_MMA(0, 0, At, B0); PG8_MMA(0, 1, At, B1); PG8_BAR; PG8_SCHED;
	s_setprio 1
	s_waitcnt lgkmcnt(0)
	v_mfma_f32_16x16x32_bf16 v[60:63], v[158:161], v[206:209], v[60:63]
	v_mfma_f32_16x16x32_bf16 v[52:55], v[166:169], v[206:209], v[52:55]
	v_mfma_f32_16x16x32_bf16 v[44:47], v[158:161], v[214:217], v[44:47]
	v_mfma_f32_16x16x32_bf16 v[36:39], v[166:169], v[214:217], v[36:39]
	v_mfma_f32_16x16x32_bf16 v[28:31], v[158:161], v[222:225], v[28:31]
	v_mfma_f32_16x16x32_bf16 v[20:23], v[166:169], v[222:225], v[20:23]
	v_mfma_f32_16x16x32_bf16 v[12:15], v[158:161], v[230:233], v[12:15]
	v_mfma_f32_16x16x32_bf16 v[4:7], v[166:169], v[230:233], v[4:7]
	v_mfma_f32_16x16x32_bf16 v[60:63], v[162:165], v[210:213], v[60:63]
	v_mfma_f32_16x16x32_bf16 v[52:55], v[170:173], v[210:213], v[52:55]
	v_mfma_f32_16x16x32_bf16 v[44:47], v[162:165], v[218:221], v[44:47]
	v_mfma_f32_16x16x32_bf16 v[36:39], v[170:173], v[218:221], v[36:39]
	v_mfma_f32_16x16x32_bf16 v[28:31], v[162:165], v[226:229], v[28:31]
	v_mfma_f32_16x16x32_bf16 v[20:23], v[170:173], v[226:229], v[20:23]
	v_mfma_f32_16x16x32_bf16 v[12:15], v[162:165], v[234:237], v[12:15]
	v_mfma_f32_16x16x32_bf16 v[4:7], v[170:173], v[234:237], v[4:7]
	v_mfma_f32_16x16x32_bf16 v[56:59], v[174:177], v[206:209], v[56:59]
	v_mfma_f32_16x16x32_bf16 v[48:51], v[182:185], v[206:209], v[48:51]
	v_mfma_f32_16x16x32_bf16 v[40:43], v[174:177], v[214:217], v[40:43]
	v_mfma_f32_16x16x32_bf16 v[32:35], v[182:185], v[214:217], v[32:35]
	v_mfma_f32_16x16x32_bf16 v[24:27], v[174:177], v[222:225], v[24:27]
	v_mfma_f32_16x16x32_bf16 v[16:19], v[182:185], v[222:225], v[16:19]
	v_mfma_f32_16x16x32_bf16 v[8:11], v[174:177], v[230:233], v[8:11]
	v_mfma_f32_16x16x32_bf16 v[0:3], v[182:185], v[230:233], v[0:3]
	v_mfma_f32_16x16x32_bf16 v[56:59], v[178:181], v[210:213], v[56:59]
	v_mfma_f32_16x16x32_bf16 v[48:51], v[186:189], v[210:213], v[48:51]
	v_mfma_f32_16x16x32_bf16 v[40:43], v[178:181], v[218:221], v[40:43]
	v_mfma_f32_16x16x32_bf16 v[32:35], v[186:189], v[218:221], v[32:35]
	v_mfma_f32_16x16x32_bf16 v[24:27], v[178:181], v[226:229], v[24:27]
	v_mfma_f32_16x16x32_bf16 v[16:19], v[186:189], v[226:229], v[16:19]
	v_mfma_f32_16x16x32_bf16 v[8:11], v[178:181], v[234:237], v[8:11]
	v_mfma_f32_16x16x32_bf16 v[0:3], v[186:189], v[234:237], v[0:3]
	s_setprio 0
	s_barrier
	s_add_i32 s23, 0, 0x18000
	s_add_i32 s86, 0, 0x1c000
	v_add_u32_e32 v170, s23, v191
	v_add_u32_e32 v186, s86, v191
	ds_read_b128 v[158:161], v170
	ds_read_b128 v[162:165], v170 offset:1024
	ds_read_b128 v[166:169], v170 offset:2048
	ds_read_b128 v[170:173], v170 offset:3072
	ds_read_b128 v[174:177], v186
	ds_read_b128 v[178:181], v186 offset:1024
	ds_read_b128 v[182:185], v186 offset:2048
	ds_read_b128 v[186:189], v186 offset:3072
	s_add_u32 s24, s50, 0x80000
	s_addc_u32 s25, s51, 0
	s_mov_b32 m0, s55
	v_lshl_add_u64 v[246:247], s[24:25], 0, v[128:129]
	ds_read_b128 v[206:209], v203 offset:32768
	ds_read_b128 v[210:213], v203 offset:33792
	ds_read_b128 v[214:217], v203 offset:34816
	ds_read_b128 v[218:221], v203 offset:35840
	ds_read_b128 v[222:225], v203 offset:36864
	ds_read_b128 v[226:229], v203 offset:37888
	ds_read_b128 v[230:233], v203 offset:38912
	ds_read_b128 v[234:237], v203 offset:39936
	global_load_lds_dwordx4 v[246:247], off
	v_lshl_add_u64 v[246:247], s[24:25], 0, v[132:133]
	s_mov_b32 m0, s56
	s_nop 0
	global_load_lds_dwordx4 v[246:247], off
	s_waitcnt vmcnt(8)
	s_waitcnt lgkmcnt(0)
	s_barrier
	s_setprio 1
	s_waitcnt lgkmcnt(0)
	v_mfma_f32_16x16x32_bf16 v[124:127], v[158:161], v[206:209], v[124:127]
	v_mfma_f32_16x16x32_bf16 v[116:119], v[166:169], v[206:209], v[116:119]
	v_mfma_f32_16x16x32_bf16 v[108:111], v[158:161], v[214:217], v[108:111]
	v_mfma_f32_16x16x32_bf16 v[100:103], v[166:169], v[214:217], v[100:103]
	v_mfma_f32_16x16x32_bf16 v[92:95], v[158:161], v[222:225], v[92:95]
	v_mfma_f32_16x16x32_bf16 v[84:87], v[166:169], v[222:225], v[84:87]
	v_mfma_f32_16x16x32_bf16 v[76:79], v[158:161], v[230:233], v[76:79]
	v_mfma_f32_16x16x32_bf16 v[68:71], v[166:169], v[230:233], v[68:71]
	v_mfma_f32_16x16x32_bf16 v[124:127], v[162:165], v[210:213], v[124:127]
	v_mfma_f32_16x16x32_bf16 v[116:119], v[170:173], v[210:213], v[116:119]
	v_mfma_f32_16x16x32_bf16 v[108:111], v[162:165], v[218:221], v[108:111]
	v_mfma_f32_16x16x32_bf16 v[100:103], v[170:173], v[218:221], v[100:103]
	v_mfma_f32_16x16x32_bf16 v[92:95], v[162:165], v[226:229], v[92:95]
	v_mfma_f32_16x16x32_bf16 v[84:87], v[170:173], v[226:229], v[84:87]
	v_mfma_f32_16x16x32_bf16 v[76:79], v[162:165], v[234:237], v[76:79]
	v_mfma_f32_16x16x32_bf16 v[68:71], v[170:173], v[234:237], v[68:71]
	v_mfma_f32_16x16x32_bf16 v[120:123], v[174:177], v[206:209], v[120:123]
	v_mfma_f32_16x16x32_bf16 v[112:115], v[182:185], v[206:209], v[112:115]
	v_mfma_f32_16x16x32_bf16 v[104:107], v[174:177], v[214:217], v[104:107]
	v_mfma_f32_16x16x32_bf16 v[96:99], v[182:185], v[214:217], v[96:99]
	v_mfma_f32_16x16x32_bf16 v[88:91], v[174:177], v[222:225], v[88:91]
	v_mfma_f32_16x16x32_bf16 v[80:83], v[182:185], v[222:225], v[80:83]
	v_mfma_f32_16x16x32_bf16 v[72:75], v[174:177], v[230:233], v[72:75]
	v_mfma_f32_16x16x32_bf16 v[64:67], v[182:185], v[230:233], v[64:67]
	v_mfma_f32_16x16x32_bf16 v[120:123], v[178:181], v[210:213], v[120:123]
	v_mfma_f32_16x16x32_bf16 v[112:115], v[186:189], v[210:213], v[112:115]
	v_mfma_f32_16x16x32_bf16 v[104:107], v[178:181], v[218:221], v[104:107]
	v_mfma_f32_16x16x32_bf16 v[96:99], v[186:189], v[218:221], v[96:99]
	v_mfma_f32_16x16x32_bf16 v[88:91], v[178:181], v[226:229], v[88:91]
	v_mfma_f32_16x16x32_bf16 v[80:83], v[186:189], v[226:229], v[80:83]
	v_mfma_f32_16x16x32_bf16 v[72:75], v[178:181], v[234:237], v[72:75]
	v_mfma_f32_16x16x32_bf16 v[64:67], v[186:189], v[234:237], v[64:67]
	s_setprio 0
	s_barrier
; #define PG8_STAGE(bufoff, gbase, voff) do { _Pragma("unroll") for (int _i = 0; _i < 2; ++_i) \
;         __builtin_amdgcn_global_load_lds((const unsigned*)((const char*)(gbase) + (voff)[_i]), (PG8_LAS unsigned*)(lds + (bufoff) + ldsw + _i * 8192), 16, 0, 0); } while (0)
; #define PG8_LDA(dst, b, h) do { _Pragma("unroll") for (int m = 0; m < 4; ++m) _Pragma("unroll") for (int k = 0; k < 2; ++k) dst[m][k] = *(const PG8_LAS bf16x8*)(lds + PG8_SA(b, h) + aoff + m * 2048 + k * 1024); } while (0)
; #define PG8_MMA(ai, bj, At, Bt) do { __builtin_amdgcn_s_setprio(1); _Pragma("unroll") for (int m = 0; m < 4; ++m) _Pragma("unroll") for (int n = 0; n < 2; ++n) _Pragma("unroll") for (int k = 0; k < 2; ++k) \
;         acc[ai][bj][m][n] = __builtin_amdgcn_mfma_f32_16x16x32_bf16(Bt[n][k], At[m][k], acc[ai][bj][m][n], 0, 0, 0); __builtin_amdgcn_s_setprio(0); } while (0)
; #define PG8_WAIT_V(n) asm volatile("s_waitcnt vmcnt(" #n ")" ::: "memory")
; #define PG8_WAIT_L(n) asm volatile("s_waitcnt lgkmcnt(" #n ")" ::: "memory")
; #define PG8_BAR __builtin_amdgcn_s_barrier()
; #define PG8_SCHED __builtin_amdgcn_sched_barrier(0)
; template <class Epi, class Sched, bool ALIGN_EPI = false, bool SP2 = false>
; __device__ __forceinline__ void gemm_phase(PG8_LAS unsigned char* lds, const Gemm g, const Sched& S, const Epi& E, const int wave_) {
;     ...
;         for (int t = 0; t < nt; t += 2) {
;     ...
;             PG8_LDA(At, 1, 1); PG8_STAGE(PG8_SB(1, 0), b3, voffB); PG8_STAGE(PG8_SB(1, 1), b3 + hstep, voffB); PG8_STAGE(PG8_SA(1, 0), a3, voffA);
;             PG8_WAIT_V(8); PG8_WAIT_L(0); PG8_BAR; PG8_MMA(1, 0, At, B0); PG8_MMA(1, 1, At, B1); PG8_BAR; PG8_SCHED;
	s_add_i32 s23, s23, s52
	v_lshl_add_u64 v[238:239], v[238:239], 0, s[34:35]
	s_mov_b32 m0, s23
	ds_read_b128 v[206:209], v203 offset:49152
	ds_read_b128 v[210:213], v203 offset:50176
	ds_read_b128 v[214:217], v203 offset:51200
	ds_read_b128 v[218:221], v203 offset:52224
	ds_read_b128 v[222:225], v203 offset:53248
	ds_read_b128 v[226:229], v203 offset:54272
	ds_read_b128 v[230:233], v203 offset:55296
	ds_read_b128 v[234:237], v203 offset:56320
	global_load_lds_dwordx4 v[238:239], off
	s_add_i32 m0, s23, 0x2000
	s_add_u32 s24, s48, 0x80080
	v_lshl_add_u64 v[238:239], v[240:241], 0, s[34:35]
	s_addc_u32 s25, s49, 0
	s_add_i32 s23, s86, s52
	global_load_lds_dwordx4 v[238:239], off
	v_lshl_add_u64 v[238:239], s[24:25], 0, v[130:131]
	s_mov_b32 m0, s23
	s_nop 0
	global_load_lds_dwordx4 v[238:239], off
	v_lshl_add_u64 v[238:239], s[24:25], 0, v[134:135]
	s_add_i32 m0, s23, 0x2000
	s_nop 0
	global_load_lds_dwordx4 v[238:239], off
	v_lshl_add_u64 v[238:239], v[242:243], 0, s[34:35]
	s_mov_b32 m0, s64
	s_nop 0
	global_load_lds_dwordx4 v[238:239], off
	v_lshl_add_u64 v[238:239], v[244:245], 0, s[34:35]
	s_mov_b32 m0, s65
	s_nop 0
	global_load_lds_dwordx4 v[238:239], off
	s_waitcnt vmcnt(8)
	s_waitcnt lgkmcnt(0)
	s_barrier
	s_setprio 1
	s_waitcnt lgkmcnt(0)
	v_mfma_f32_16x16x32_bf16 v[60:63], v[158:161], v[206:209], v[60:63]
	v_mfma_f32_16x16x32_bf16 v[52:55], v[166:169], v[206:209], v[52:55]
	v_mfma_f32_16x16x32_bf16 v[44:47], v[158:161], v[214:217], v[44:47]
	v_mfma_f32_16x16x32_bf16 v[36:39], v[166:169], v[214:217], v[36:39]
	v_mfma_f32_16x16x32_bf16 v[28:31], v[158:161], v[222:225], v[28:31]
	v_mfma_f32_16x16x32_bf16 v[20:23], v[166:169], v[222:225], v[20:23]
	v_mfma_f32_16x16x32_bf16 v[12:15], v[158:161], v[230:233], v[12:15]
	v_mfma_f32_16x16x32_bf16 v[4:7], v[166:169], v[230:233], v[4:7]
	v_mfma_f32_16x16x32_bf16 v[60:63], v[162:165], v[210:213], v[60:63]
	v_mfma_f32_16x16x32_bf16 v[52:55], v[170:173], v[210:213], v[52:55]
	v_mfma_f32_16x16x32_bf16 v[44:47], v[162:165], v[218:221], v[44:47]
	v_mfma_f32_16x16x32_bf16 v[36:39], v[170:173], v[218:221], v[36:39]
	v_mfma_f32_16x16x32_bf16 v[28:31], v[162:165], v[226:229], v[28:31]
	v_mfma_f32_16x16x32_bf16 v[20:23], v[170:173], v[226:229], v[20:23]
	v_mfma_f32_16x16x32_bf16 v[12:15], v[162:165], v[234:237], v[12:15]
	v_mfma_f32_16x16x32_bf16 v[4:7], v[170:173], v[234:237], v[4:7]
	v_mfma_f32_16x16x32_bf16 v[56:59], v[174:177], v[206:209], v[56:59]
	v_mfma_f32_16x16x32_bf16 v[48:51], v[182:185], v[206:209], v[48:51]
	v_mfma_f32_16x16x32_bf16 v[40:43], v[174:177], v[214:217], v[40:43]
	v_mfma_f32_16x16x32_bf16 v[32:35], v[182:185], v[214:217], v[32:35]
	v_mfma_f32_16x16x32_bf16 v[24:27], v[174:177], v[222:225], v[24:27]
	v_mfma_f32_16x16x32_bf16 v[16:19], v[182:185], v[222:225], v[16:19]
	v_mfma_f32_16x16x32_bf16 v[8:11], v[174:177], v[230:233], v[8:11]
	v_mfma_f32_16x16x32_bf16 v[0:3], v[182:185], v[230:233], v[0:3]
	v_mfma_f32_16x16x32_bf16 v[56:59], v[178:181], v[210:213], v[56:59]
	v_mfma_f32_16x16x32_bf16 v[48:51], v[186:189], v[210:213], v[48:51]
	v_mfma_f32_16x16x32_bf16 v[40:43], v[178:181], v[218:221], v[40:43]
	v_mfma_f32_16x16x32_bf16 v[32:35], v[186:189], v[218:221], v[32:35]
	v_mfma_f32_16x16x32_bf16 v[24:27], v[178:181], v[226:229], v[24:27]
	v_mfma_f32_16x16x32_bf16 v[16:19], v[186:189], v[226:229], v[16:19]
	v_mfma_f32_16x16x32_bf16 v[8:11], v[178:181], v[234:237], v[8:11]
	v_mfma_f32_16x16x32_bf16 v[0:3], v[186:189], v[234:237], v[0:3]
	s_setprio 0
	s_barrier
	s_add_i32 s22, s22, 2
	s_add_u32 s46, s46, 0x100
	s_addc_u32 s47, s47, 0
	s_add_u32 vcc_hi, vcc_hi, 0x100
	s_addc_u32 s97, s97, 0
	s_cmp_gt_u32 s22, 29
	s_cbranch_scc0 .LBB0_129
	s_and_b64 vcc, exec, s[74:75]
	s_cbranch_vccz .LBB0_132
	s_barrier

; #define PG8_STAGE(bufoff, gbase, voff) do { _Pragma("unroll") for (int _i = 0; _i < 2; ++_i) \
;         __builtin_amdgcn_global_load_lds((const unsigned*)((const char*)(gbase) + (voff)[_i]), (PG8_LAS unsigned*)(lds + (bufoff) + ldsw + _i * 8192), 16, 0, 0); } while (0)
; #define PG8_LDA(dst, b, h) do { _Pragma("unroll") for (int m = 0; m < 4; ++m) _Pragma("unroll") for (int k = 0; k < 2; ++k) dst[m][k] = *(const PG8_LAS bf16x8*)(lds + PG8_SA(b, h) + aoff + m * 2048 + k * 1024); } while (0)
; #define PG8_LDB(dst, b, h) do { _Pragma("unroll") for (int n = 0; n < 2; ++n) _Pragma("unroll") for (int k = 0; k < 2; ++k) dst[n][k] = *(const PG8_LAS bf16x8*)(lds + PG8_SB(b, h) + boff + n * 2048 + k * 1024); } while (0)
; #define PG8_MMA(ai, bj, At, Bt) do { __builtin_amdgcn_s_setprio(1); _Pragma("unroll") for (int m = 0; m < 4; ++m) _Pragma("unroll") for (int n = 0; n < 2; ++n) _Pragma("unroll") for (int k = 0; k < 2; ++k) \
;         acc[ai][bj][m][n] = __builtin_amdgcn_mfma_f32_16x16x32_bf16(Bt[n][k], At[m][k], acc[ai][bj][m][n], 0, 0, 0); __builtin_amdgcn_s_setprio(0); } while (0)
; #define PG8_WAIT_V(n) asm volatile("s_waitcnt vmcnt(" #n ")" ::: "memory")
; #define PG8_WAIT_L(n) asm volatile("s_waitcnt lgkmcnt(" #n ")" ::: "memory")
; template <class Epi, class Sched, bool ALIGN_EPI = false, bool SP2 = false>
; __device__ __forceinline__ void gemm_phase(PG8_LAS unsigned char* lds, const Gemm g, const Sched& S, const Epi& E, const int wave_) {
;     ...
;             const bool last = (t == nt - 2);
;             const char* a1 = cA + (size_t)(t + 1) * kstep;
;             const char* a2 = last ? nA : cA + (size_t)(t + 2) * kstep; const char* b2 = last ? nB : cB + (size_t)(t + 2) * kstep;
;             const char* a3 = a2 + kstep; const char* b3 = b2 + kstep;
;             if (last && has_next) S.a_ready(nxt);
;             if constexpr (SP2) {
;             PG8_LDB(B0, 0, 0); PG8_LDB(B1, 0, 1); PG8_SCHED; PG8_LDA(At, 0, 0); PG8_STAGE(PG8_SA(1, 1), a1 + hstep, voffA);
;             PG8_WAIT_V(8); PG8_WAIT_L(0); PG8_BAR; PG8_MMA(0, 0, At, B0); PG8_MMA(0, 1, At, B1); PG8_BAR; PG8_SCHED;
;             PG8_LDA(At, 0, 1); PG8_STAGE(PG8_SB(0, 0), b2, voffB); PG8_STAGE(PG8_SB(0, 1), b2 + hstep, voffB); PG8_STAGE(PG8_SA(0, 0), a2, voffA);
;             PG8_WAIT_V(8); PG8_WAIT_L(0); PG8_BAR; PG8_MMA(1, 0, At, B0); PG8_MMA(1, 1, At, B1); PG8_BAR; PG8_SCHED;
.LBB0_402:
	ds_read_b128 v[128:131], v189
	ds_read_b128 v[132:135], v189 offset:1024
	ds_read_b128 v[136:139], v189 offset:2048
	ds_read_b128 v[140:143], v189 offset:3072
	ds_read_b128 v[144:147], v201
	ds_read_b128 v[148:151], v201 offset:1024
	ds_read_b128 v[180:183], v201 offset:2048
	ds_read_b128 v[184:187], v201 offset:3072
	s_add_u32 s30, s28, 0xfff00080
	s_addc_u32 s31, s29, -1
	s_cmp_eq_u32 s53, 60
	s_cselect_b32 s35, s19, s31
	s_cselect_b32 s34, s25, s30
	s_cselect_b32 s31, s17, s52
	s_cselect_b32 s30, s50, s51
	v_lshl_add_u64 v[170:171], s[28:29], 0, v[162:163]
	s_add_i32 m0, s27, 0xc000
	ds_read_b128 v[190:193], v202
	ds_read_b128 v[196:199], v202 offset:1024
	ds_read_b128 v[204:207], v202 offset:2048
	ds_read_b128 v[208:211], v202 offset:3072
	ds_read_b128 v[212:215], v202 offset:4096
	ds_read_b128 v[216:219], v202 offset:5120
	ds_read_b128 v[220:223], v202 offset:6144
	ds_read_b128 v[224:227], v202 offset:7168
	global_load_lds_dwordx4 v[170:171], off
	v_lshl_add_u64 v[170:171], s[28:29], 0, v[164:165]
	s_add_i32 m0, s27, 0xe000
	s_nop 0
	global_load_lds_dwordx4 v[170:171], off
	s_waitcnt vmcnt(8)
	s_waitcnt lgkmcnt(0)
	s_barrier
	s_setprio 1
	s_waitcnt lgkmcnt(0)
	v_mfma_f32_16x16x32_bf16 v[124:127], v[128:131], v[190:193], v[124:127]
	v_mfma_f32_16x16x32_bf16 v[120:123], v[136:139], v[190:193], v[120:123]
	v_mfma_f32_16x16x32_bf16 v[108:111], v[128:131], v[204:207], v[108:111]
	v_mfma_f32_16x16x32_bf16 v[104:107], v[136:139], v[204:207], v[104:107]
	v_mfma_f32_16x16x32_bf16 v[92:95], v[128:131], v[212:215], v[92:95]
	v_mfma_f32_16x16x32_bf16 v[88:91], v[136:139], v[212:215], v[88:91]
	v_mfma_f32_16x16x32_bf16 v[76:79], v[128:131], v[220:223], v[76:79]
	v_mfma_f32_16x16x32_bf16 v[72:75], v[136:139], v[220:223], v[72:75]
	v_mfma_f32_16x16x32_bf16 v[124:127], v[132:135], v[196:199], v[124:127]
	v_mfma_f32_16x16x32_bf16 v[120:123], v[140:143], v[196:199], v[120:123]
	v_mfma_f32_16x16x32_bf16 v[108:111], v[132:135], v[208:211], v[108:111]
	v_mfma_f32_16x16x32_bf16 v[104:107], v[140:143], v[208:211], v[104:107]
	v_mfma_f32_16x16x32_bf16 v[92:95], v[132:135], v[216:219], v[92:95]
	v_mfma_f32_16x16x32_bf16 v[88:91], v[140:143], v[216:219], v[88:91]
	v_mfma_f32_16x16x32_bf16 v[76:79], v[132:135], v[224:227], v[76:79]
	v_mfma_f32_16x16x32_bf16 v[72:75], v[140:143], v[224:227], v[72:75]
	v_mfma_f32_16x16x32_bf16 v[116:119], v[144:147], v[190:193], v[116:119]
	v_mfma_f32_16x16x32_bf16 v[112:115], v[180:183], v[190:193], v[112:115]
	v_mfma_f32_16x16x32_bf16 v[100:103], v[144:147], v[204:207], v[100:103]
	v_mfma_f32_16x16x32_bf16 v[96:99], v[180:183], v[204:207], v[96:99]
	v_mfma_f32_16x16x32_bf16 v[84:87], v[144:147], v[212:215], v[84:87]
	v_mfma_f32_16x16x32_bf16 v[80:83], v[180:183], v[212:215], v[80:83]
	v_mfma_f32_16x16x32_bf16 v[68:71], v[144:147], v[220:223], v[68:71]
	v_mfma_f32_16x16x32_bf16 v[64:67], v[180:183], v[220:223], v[64:67]
	v_mfma_f32_16x16x32_bf16 v[116:119], v[148:151], v[196:199], v[116:119]
	v_mfma_f32_16x16x32_bf16 v[112:115], v[184:187], v[196:199], v[112:115]
	v_mfma_f32_16x16x32_bf16 v[100:103], v[148:151], v[208:211], v[100:103]
	v_mfma_f32_16x16x32_bf16 v[96:99], v[184:187], v[208:211], v[96:99]
	v_mfma_f32_16x16x32_bf16 v[84:87], v[148:151], v[216:219], v[84:87]
	v_mfma_f32_16x16x32_bf16 v[80:83], v[184:187], v[216:219], v[80:83]
	v_mfma_f32_16x16x32_bf16 v[68:71], v[148:151], v[224:227], v[68:71]
	v_mfma_f32_16x16x32_bf16 v[64:67], v[184:187], v[224:227], v[64:67]
	s_setprio 0
	s_barrier
	s_add_i32 s54, s48, s36
	v_lshl_add_u64 v[170:171], s[30:31], 0, v[156:157]
	s_mov_b32 m0, s54
	ds_read_b128 v[190:193], v202 offset:16384
	ds_read_b128 v[196:199], v202 offset:17408
	ds_read_b128 v[204:207], v202 offset:18432
	ds_read_b128 v[208:211], v202 offset:19456
	ds_read_b128 v[212:215], v202 offset:20480
	ds_read_b128 v[216:219], v202 offset:21504
	ds_read_b128 v[220:223], v202 offset:22528
	ds_read_b128 v[224:227], v202 offset:23552
	global_load_lds_dwordx4 v[170:171], off
	s_add_i32 m0, s54, 0x2000
	s_add_u32 s54, s30, 0x100000
	v_lshl_add_u64 v[228:229], s[30:31], 0, v[160:161]
	s_addc_u32 s55, s31, 0
	s_add_i32 s56, s49, s36
	global_load_lds_dwordx4 v[228:229], off
	v_lshl_add_u64 v[230:231], s[54:55], 0, v[156:157]
	s_mov_b32 m0, s56
	v_lshl_add_u64 v[232:233], s[34:35], 0, v[158:159]
	global_load_lds_dwordx4 v[230:231], off
	v_lshl_add_u64 v[230:231], s[54:55], 0, v[160:161]
	s_add_i32 m0, s56, 0x2000
	s_nop 0
	global_load_lds_dwordx4 v[230:231], off
	v_lshl_add_u64 v[230:231], s[34:35], 0, v[154:155]
	s_mov_b32 m0, s27
	s_nop 0
	global_load_lds_dwordx4 v[230:231], off
	s_mov_b32 m0, s37
	s_nop 0
	global_load_lds_dwordx4 v[232:233], off
	s_waitcnt vmcnt(8)
	s_waitcnt lgkmcnt(0)
	s_barrier
; #define PG8_STAGE(bufoff, gbase, voff) do { _Pragma("unroll") for (int _i = 0; _i < 2; ++_i) \
;         __builtin_amdgcn_global_load_lds((const unsigned*)((const char*)(gbase) + (voff)[_i]), (PG8_LAS unsigned*)(lds + (bufoff) + ldsw + _i * 8192), 16, 0, 0); } while (0)
; #define PG8_LDA(dst, b, h) do { _Pragma("unroll") for (int m = 0; m < 4; ++m) _Pragma("unroll") for (int k = 0; k < 2; ++k) dst[m][k] = *(const PG8_LAS bf16x8*)(lds + PG8_SA(b, h) + aoff + m * 2048 + k * 1024); } while (0)
; #define PG8_LDB(dst, b, h) do { _Pragma("unroll") for (int n = 0; n < 2; ++n) _Pragma("unroll") for (int k = 0; k < 2; ++k) dst[n][k] = *(const PG8_LAS bf16x8*)(lds + PG8_SB(b, h) + boff + n * 2048 + k * 1024); } while (0)
; #define PG8_MMA(ai, bj, At, Bt) do { __builtin_amdgcn_s_setprio(1); _Pragma("unroll") for (int m = 0; m < 4; ++m) _Pragma("unroll") for (int n = 0; n < 2; ++n) _Pragma("unroll") for (int k = 0; k < 2; ++k) \
;         acc[ai][bj][m][n] = __builtin_amdgcn_mfma_f32_16x16x32_bf16(Bt[n][k], At[m][k], acc[ai][bj][m][n], 0, 0, 0); __builtin_amdgcn_s_setprio(0); } while (0)
; #define PG8_WAIT_V(n) asm volatile("s_waitcnt vmcnt(" #n ")" ::: "memory")
; #define PG8_WAIT_L(n) asm volatile("s_waitcnt lgkmcnt(" #n ")" ::: "memory")
; #define PG8_BAR __builtin_amdgcn_s_barrier()
; #define PG8_SCHED __builtin_amdgcn_sched_barrier(0)
; template <class Epi, class Sched, bool ALIGN_EPI = false, bool SP2 = false>
; __device__ __forceinline__ void gemm_phase(PG8_LAS unsigned char* lds, const Gemm g, const Sched& S, const Epi& E, const int wave_) {
;     ...
;             PG8_WAIT_V(8); PG8_WAIT_L(0); PG8_BAR; PG8_MMA(1, 0, At, B0); PG8_MMA(1, 1, At, B1); PG8_BAR; PG8_SCHED;
;             PG8_LDB(B0, 1, 0); PG8_LDB(B1, 1, 1); PG8_SCHED; PG8_LDA(At, 1, 0); PG8_STAGE(PG8_SA(0, 1), a2 + hstep, voffA);
;             PG8_WAIT_V(8); PG8_WAIT_L(0); PG8_BAR; PG8_MMA(0, 0, At, B0); PG8_MMA(0, 1, At, B1); PG8_BAR; PG8_SCHED;
	s_setprio 1
	s_waitcnt lgkmcnt(0)
	v_mfma_f32_16x16x32_bf16 v[60:63], v[128:131], v[190:193], v[60:63]
	v_mfma_f32_16x16x32_bf16 v[56:59], v[136:139], v[190:193], v[56:59]
	v_mfma_f32_16x16x32_bf16 v[44:47], v[128:131], v[204:207], v[44:47]
	v_mfma_f32_16x16x32_bf16 v[40:43], v[136:139], v[204:207], v[40:43]
	v_mfma_f32_16x16x32_bf16 v[28:31], v[128:131], v[212:215], v[28:31]
	v_mfma_f32_16x16x32_bf16 v[24:27], v[136:139], v[212:215], v[24:27]
	v_mfma_f32_16x16x32_bf16 v[12:15], v[128:131], v[220:223], v[12:15]
	v_mfma_f32_16x16x32_bf16 v[8:11], v[136:139], v[220:223], v[8:11]
	v_mfma_f32_16x16x32_bf16 v[60:63], v[132:135], v[196:199], v[60:63]
	v_mfma_f32_16x16x32_bf16 v[56:59], v[140:143], v[196:199], v[56:59]
	v_mfma_f32_16x16x32_bf16 v[44:47], v[132:135], v[208:211], v[44:47]
	v_mfma_f32_16x16x32_bf16 v[40:43], v[140:143], v[208:211], v[40:43]
	v_mfma_f32_16x16x32_bf16 v[28:31], v[132:135], v[216:219], v[28:31]
	v_mfma_f32_16x16x32_bf16 v[24:27], v[140:143], v[216:219], v[24:27]
	v_mfma_f32_16x16x32_bf16 v[12:15], v[132:135], v[224:227], v[12:15]
	v_mfma_f32_16x16x32_bf16 v[8:11], v[140:143], v[224:227], v[8:11]
	v_mfma_f32_16x16x32_bf16 v[52:55], v[144:147], v[190:193], v[52:55]
	v_mfma_f32_16x16x32_bf16 v[48:51], v[180:183], v[190:193], v[48:51]
	v_mfma_f32_16x16x32_bf16 v[36:39], v[144:147], v[204:207], v[36:39]
	v_mfma_f32_16x16x32_bf16 v[32:35], v[180:183], v[204:207], v[32:35]
	v_mfma_f32_16x16x32_bf16 v[20:23], v[144:147], v[212:215], v[20:23]
	v_mfma_f32_16x16x32_bf16 v[16:19], v[180:183], v[212:215], v[16:19]
	v_mfma_f32_16x16x32_bf16 v[4:7], v[144:147], v[220:223], v[4:7]
	v_mfma_f32_16x16x32_bf16 v[0:3], v[180:183], v[220:223], v[0:3]
	v_mfma_f32_16x16x32_bf16 v[52:55], v[148:151], v[196:199], v[52:55]
	v_mfma_f32_16x16x32_bf16 v[48:51], v[184:187], v[196:199], v[48:51]
	v_mfma_f32_16x16x32_bf16 v[36:39], v[148:151], v[208:211], v[36:39]
	v_mfma_f32_16x16x32_bf16 v[32:35], v[184:187], v[208:211], v[32:35]
	v_mfma_f32_16x16x32_bf16 v[20:23], v[148:151], v[216:219], v[20:23]
	v_mfma_f32_16x16x32_bf16 v[16:19], v[184:187], v[216:219], v[16:19]
	v_mfma_f32_16x16x32_bf16 v[4:7], v[148:151], v[224:227], v[4:7]
	v_mfma_f32_16x16x32_bf16 v[0:3], v[184:187], v[224:227], v[0:3]
	s_setprio 0
	s_barrier
	s_add_i32 s54, 0, 0x18000
	s_add_i32 s55, 0, 0x1c000
	v_add_u32_e32 v140, s54, v173
	v_add_u32_e32 v172, s55, v173
	ds_read_b128 v[128:131], v140
	ds_read_b128 v[132:135], v140 offset:1024
	ds_read_b128 v[136:139], v140 offset:2048
	ds_read_b128 v[140:143], v140 offset:3072
	ds_read_b128 v[144:147], v172
	ds_read_b128 v[148:151], v172 offset:1024
	ds_read_b128 v[180:183], v172 offset:2048
	ds_read_b128 v[184:187], v172 offset:3072
	s_add_u32 s34, s34, 0x100000
	s_addc_u32 s35, s35, 0
	s_mov_b32 m0, s40
	v_lshl_add_u64 v[234:235], s[34:35], 0, v[154:155]
	ds_read_b128 v[190:193], v202 offset:32768
	ds_read_b128 v[196:199], v202 offset:33792
	ds_read_b128 v[204:207], v202 offset:34816
	ds_read_b128 v[208:211], v202 offset:35840
	ds_read_b128 v[212:215], v202 offset:36864
	ds_read_b128 v[216:219], v202 offset:37888
	ds_read_b128 v[220:223], v202 offset:38912
	ds_read_b128 v[224:227], v202 offset:39936
	global_load_lds_dwordx4 v[234:235], off
	v_lshl_add_u64 v[234:235], s[34:35], 0, v[158:159]
	s_mov_b32 m0, s41
	s_nop 0
	global_load_lds_dwordx4 v[234:235], off
	s_waitcnt vmcnt(8)
	s_waitcnt lgkmcnt(0)
	s_barrier
	s_setprio 1
	s_waitcnt lgkmcnt(0)
	v_mfma_f32_16x16x32_bf16 v[124:127], v[128:131], v[190:193], v[124:127]
	v_mfma_f32_16x16x32_bf16 v[120:123], v[136:139], v[190:193], v[120:123]
	v_mfma_f32_16x16x32_bf16 v[108:111], v[128:131], v[204:207], v[108:111]
	v_mfma_f32_16x16x32_bf16 v[104:107], v[136:139], v[204:207], v[104:107]
	v_mfma_f32_16x16x32_bf16 v[92:95], v[128:131], v[212:215], v[92:95]
	v_mfma_f32_16x16x32_bf16 v[88:91], v[136:139], v[212:215], v[88:91]
	v_mfma_f32_16x16x32_bf16 v[76:79], v[128:131], v[220:223], v[76:79]
	v_mfma_f32_16x16x32_bf16 v[72:75], v[136:139], v[220:223], v[72:75]
	v_mfma_f32_16x16x32_bf16 v[124:127], v[132:135], v[196:199], v[124:127]
	v_mfma_f32_16x16x32_bf16 v[120:123], v[140:143], v[196:199], v[120:123]
	v_mfma_f32_16x16x32_bf16 v[108:111], v[132:135], v[208:211], v[108:111]
	v_mfma_f32_16x16x32_bf16 v[104:107], v[140:143], v[208:211], v[104:107]
	v_mfma_f32_16x16x32_bf16 v[92:95], v[132:135], v[216:219], v[92:95]
	v_mfma_f32_16x16x32_bf16 v[88:91], v[140:143], v[216:219], v[88:91]
	v_mfma_f32_16x16x32_bf16 v[76:79], v[132:135], v[224:227], v[76:79]
	v_mfma_f32_16x16x32_bf16 v[72:75], v[140:143], v[224:227], v[72:75]
	v_mfma_f32_16x16x32_bf16 v[116:119], v[144:147], v[190:193], v[116:119]
	v_mfma_f32_16x16x32_bf16 v[112:115], v[180:183], v[190:193], v[112:115]
	v_mfma_f32_16x16x32_bf16 v[100:103], v[144:147], v[204:207], v[100:103]
	v_mfma_f32_16x16x32_bf16 v[96:99], v[180:183], v[204:207], v[96:99]
	v_mfma_f32_16x16x32_bf16 v[84:87], v[144:147], v[212:215], v[84:87]
	v_mfma_f32_16x16x32_bf16 v[80:83], v[180:183], v[212:215], v[80:83]
	v_mfma_f32_16x16x32_bf16 v[68:71], v[144:147], v[220:223], v[68:71]
	v_mfma_f32_16x16x32_bf16 v[64:67], v[180:183], v[220:223], v[64:67]
	v_mfma_f32_16x16x32_bf16 v[116:119], v[148:151], v[196:199], v[116:119]
	v_mfma_f32_16x16x32_bf16 v[112:115], v[184:187], v[196:199], v[112:115]
	v_mfma_f32_16x16x32_bf16 v[100:103], v[148:151], v[208:211], v[100:103]
	v_mfma_f32_16x16x32_bf16 v[96:99], v[184:187], v[208:211], v[96:99]
	v_mfma_f32_16x16x32_bf16 v[84:87], v[148:151], v[216:219], v[84:87]
	v_mfma_f32_16x16x32_bf16 v[80:83], v[184:187], v[216:219], v[80:83]
	v_mfma_f32_16x16x32_bf16 v[68:71], v[148:151], v[224:227], v[68:71]
	v_mfma_f32_16x16x32_bf16 v[64:67], v[184:187], v[224:227], v[64:67]
	s_setprio 0
	s_barrier
; #define PG8_STAGE(bufoff, gbase, voff) do { _Pragma("unroll") for (int _i = 0; _i < 2; ++_i) \
;         __builtin_amdgcn_global_load_lds((const unsigned*)((const char*)(gbase) + (voff)[_i]), (PG8_LAS unsigned*)(lds + (bufoff) + ldsw + _i * 8192), 16, 0, 0); } while (0)
; #define PG8_LDA(dst, b, h) do { _Pragma("unroll") for (int m = 0; m < 4; ++m) _Pragma("unroll") for (int k = 0; k < 2; ++k) dst[m][k] = *(const PG8_LAS bf16x8*)(lds + PG8_SA(b, h) + aoff + m * 2048 + k * 1024); } while (0)
; #define PG8_MMA(ai, bj, At, Bt) do { __builtin_amdgcn_s_setprio(1); _Pragma("unroll") for (int m = 0; m < 4; ++m) _Pragma("unroll") for (int n = 0; n < 2; ++n) _Pragma("unroll") for (int k = 0; k < 2; ++k) \
;         acc[ai][bj][m][n] = __builtin_amdgcn_mfma_f32_16x16x32_bf16(Bt[n][k], At[m][k], acc[ai][bj][m][n], 0, 0, 0); __builtin_amdgcn_s_setprio(0); } while (0)
; #define PG8_WAIT_V(n) asm volatile("s_waitcnt vmcnt(" #n ")" ::: "memory")
; #define PG8_WAIT_L(n) asm volatile("s_waitcnt lgkmcnt(" #n ")" ::: "memory")
; #define PG8_BAR __builtin_amdgcn_s_barrier()
; #define PG8_SCHED __builtin_amdgcn_sched_barrier(0)
; template <class Epi, class Sched, bool ALIGN_EPI = false, bool SP2 = false>
; __device__ __forceinline__ void gemm_phase(PG8_LAS unsigned char* lds, const Gemm g, const Sched& S, const Epi& E, const int wave_) {
;     ...
;         for (int t = 0; t < nt; t += 2) {
;             const bool last = (t == nt - 2);
;             const char* a1 = cA + (size_t)(t + 1) * kstep;
;             const char* a2 = last ? nA : cA + (size_t)(t + 2) * kstep; const char* b2 = last ? nB : cB + (size_t)(t + 2) * kstep;
;             const char* a3 = a2 + kstep; const char* b3 = b2 + kstep;
;     ...
;             PG8_LDA(At, 1, 1); PG8_STAGE(PG8_SB(1, 0), b3, voffB); PG8_STAGE(PG8_SB(1, 1), b3 + hstep, voffB); PG8_STAGE(PG8_SA(1, 0), a3, voffA);
;             PG8_WAIT_V(8); PG8_WAIT_L(0); PG8_BAR; PG8_MMA(1, 0, At, B0); PG8_MMA(1, 1, At, B1); PG8_BAR; PG8_SCHED;
	s_add_i32 s34, s54, s36
	v_lshl_add_u64 v[170:171], v[170:171], 0, s[14:15]
	s_mov_b32 m0, s34
	ds_read_b128 v[190:193], v202 offset:49152
	ds_read_b128 v[196:199], v202 offset:50176
	ds_read_b128 v[204:207], v202 offset:51200
	ds_read_b128 v[208:211], v202 offset:52224
	ds_read_b128 v[212:215], v202 offset:53248
	ds_read_b128 v[216:219], v202 offset:54272
	ds_read_b128 v[220:223], v202 offset:55296
	ds_read_b128 v[224:227], v202 offset:56320
	global_load_lds_dwordx4 v[170:171], off
	s_add_i32 m0, s34, 0x2000
	s_add_u32 s30, s30, 0x100080
	v_lshl_add_u64 v[170:171], v[228:229], 0, s[14:15]
	s_addc_u32 s31, s31, 0
	s_add_i32 s34, s55, s36
	global_load_lds_dwordx4 v[170:171], off
	v_lshl_add_u64 v[170:171], s[30:31], 0, v[156:157]
	s_mov_b32 m0, s34
	s_nop 0
	global_load_lds_dwordx4 v[170:171], off
	v_lshl_add_u64 v[170:171], s[30:31], 0, v[160:161]
	s_add_i32 m0, s34, 0x2000
	s_nop 0
	global_load_lds_dwordx4 v[170:171], off
	v_lshl_add_u64 v[170:171], v[230:231], 0, s[14:15]
	s_mov_b32 m0, s45
	s_nop 0
	global_load_lds_dwordx4 v[170:171], off
	v_lshl_add_u64 v[170:171], v[232:233], 0, s[14:15]
	s_mov_b32 m0, s46
	s_nop 0
	global_load_lds_dwordx4 v[170:171], off
	s_waitcnt vmcnt(8)
	s_waitcnt lgkmcnt(0)
	s_barrier
	s_setprio 1
	s_waitcnt lgkmcnt(0)
	v_mfma_f32_16x16x32_bf16 v[60:63], v[128:131], v[190:193], v[60:63]
	v_mfma_f32_16x16x32_bf16 v[56:59], v[136:139], v[190:193], v[56:59]
	v_mfma_f32_16x16x32_bf16 v[44:47], v[128:131], v[204:207], v[44:47]
	v_mfma_f32_16x16x32_bf16 v[40:43], v[136:139], v[204:207], v[40:43]
	v_mfma_f32_16x16x32_bf16 v[28:31], v[128:131], v[212:215], v[28:31]
	v_mfma_f32_16x16x32_bf16 v[24:27], v[136:139], v[212:215], v[24:27]
	v_mfma_f32_16x16x32_bf16 v[12:15], v[128:131], v[220:223], v[12:15]
	v_mfma_f32_16x16x32_bf16 v[8:11], v[136:139], v[220:223], v[8:11]
	v_mfma_f32_16x16x32_bf16 v[60:63], v[132:135], v[196:199], v[60:63]
	v_mfma_f32_16x16x32_bf16 v[56:59], v[140:143], v[196:199], v[56:59]
	v_mfma_f32_16x16x32_bf16 v[44:47], v[132:135], v[208:211], v[44:47]
	v_mfma_f32_16x16x32_bf16 v[40:43], v[140:143], v[208:211], v[40:43]
	v_mfma_f32_16x16x32_bf16 v[28:31], v[132:135], v[216:219], v[28:31]
	v_mfma_f32_16x16x32_bf16 v[24:27], v[140:143], v[216:219], v[24:27]
	v_mfma_f32_16x16x32_bf16 v[12:15], v[132:135], v[224:227], v[12:15]
	v_mfma_f32_16x16x32_bf16 v[8:11], v[140:143], v[224:227], v[8:11]
	v_mfma_f32_16x16x32_bf16 v[52:55], v[144:147], v[190:193], v[52:55]
	v_mfma_f32_16x16x32_bf16 v[48:51], v[180:183], v[190:193], v[48:51]
	v_mfma_f32_16x16x32_bf16 v[36:39], v[144:147], v[204:207], v[36:39]
	v_mfma_f32_16x16x32_bf16 v[32:35], v[180:183], v[204:207], v[32:35]
	v_mfma_f32_16x16x32_bf16 v[20:23], v[144:147], v[212:215], v[20:23]
	v_mfma_f32_16x16x32_bf16 v[16:19], v[180:183], v[212:215], v[16:19]
	v_mfma_f32_16x16x32_bf16 v[4:7], v[144:147], v[220:223], v[4:7]
	v_mfma_f32_16x16x32_bf16 v[0:3], v[180:183], v[220:223], v[0:3]
	v_mfma_f32_16x16x32_bf16 v[52:55], v[148:151], v[196:199], v[52:55]
	v_mfma_f32_16x16x32_bf16 v[48:51], v[184:187], v[196:199], v[48:51]
	v_mfma_f32_16x16x32_bf16 v[36:39], v[148:151], v[208:211], v[36:39]
	v_mfma_f32_16x16x32_bf16 v[32:35], v[184:187], v[208:211], v[32:35]
	v_mfma_f32_16x16x32_bf16 v[20:23], v[148:151], v[216:219], v[20:23]
	v_mfma_f32_16x16x32_bf16 v[16:19], v[184:187], v[216:219], v[16:19]
	v_mfma_f32_16x16x32_bf16 v[4:7], v[148:151], v[224:227], v[4:7]
	v_mfma_f32_16x16x32_bf16 v[0:3], v[184:187], v[224:227], v[0:3]
	s_setprio 0
	s_barrier
	s_add_i32 s53, s53, 2
	s_add_u32 s28, s28, 0x100
	s_addc_u32 s29, s29, 0
	s_add_u32 s51, s51, 0x100
	s_addc_u32 s52, s52, 0
	s_cmp_gt_u32 s53, 61
	s_cbranch_scc0 .LBB0_402
	s_and_b64 vcc, exec, s[12:13]
	s_cbranch_vccz .LBB0_405
	s_barrier

; #define PG8_STAGE(bufoff, gbase, voff) do { _Pragma("unroll") for (int _i = 0; _i < 2; ++_i) \
;         __builtin_amdgcn_global_load_lds((const unsigned*)((const char*)(gbase) + (voff)[_i]), (PG8_LAS unsigned*)(lds + (bufoff) + ldsw + _i * 8192), 16, 0, 0); } while (0)
; #define PG8_LDA(dst, b, h) do { _Pragma("unroll") for (int m = 0; m < 4; ++m) _Pragma("unroll") for (int k = 0; k < 2; ++k) dst[m][k] = *(const PG8_LAS bf16x8*)(lds + PG8_SA(b, h) + aoff + m * 2048 + k * 1024); } while (0)
; #define PG8_LDB(dst, b, h) do { _Pragma("unroll") for (int n = 0; n < 2; ++n) _Pragma("unroll") for (int k = 0; k < 2; ++k) dst[n][k] = *(const PG8_LAS bf16x8*)(lds + PG8_SB(b, h) + boff + n * 2048 + k * 1024); } while (0)
; #define PG8_MMA(ai, bj, At, Bt) do { __builtin_amdgcn_s_setprio(1); _Pragma("unroll") for (int m = 0; m < 4; ++m) _Pragma("unroll") for (int n = 0; n < 2; ++n) _Pragma("unroll") for (int k = 0; k < 2; ++k) \
;         acc[ai][bj][m][n] = __builtin_amdgcn_mfma_f32_16x16x32_bf16(Bt[n][k], At[m][k], acc[ai][bj][m][n], 0, 0, 0); __builtin_amdgcn_s_setprio(0); } while (0)
; #define PG8_WAIT_V(n) asm volatile("s_waitcnt vmcnt(" #n ")" ::: "memory")
; #define PG8_WAIT_L(n) asm volatile("s_waitcnt lgkmcnt(" #n ")" ::: "memory")
; template <class Epi, class Sched, bool ALIGN_EPI = false, bool SP2 = false>
; __device__ __forceinline__ void gemm_phase(PG8_LAS unsigned char* lds, const Gemm g, const Sched& S, const Epi& E, const int wave_) {
;     ...
;             const bool last = (t == nt - 2);
;             const char* a1 = cA + (size_t)(t + 1) * kstep;
;             const char* a2 = last ? nA : cA + (size_t)(t + 2) * kstep; const char* b2 = last ? nB : cB + (size_t)(t + 2) * kstep;
;             const char* a3 = a2 + kstep; const char* b3 = b2 + kstep;
;             if (last && has_next) S.a_ready(nxt);
;             if constexpr (SP2) {
;             PG8_LDB(B0, 0, 0); PG8_LDB(B1, 0, 1); PG8_SCHED; PG8_LDA(At, 0, 0); PG8_STAGE(PG8_SA(1, 1), a1 + hstep, voffA);
;             PG8_WAIT_V(8); PG8_WAIT_L(0); PG8_BAR; PG8_MMA(0, 0, At, B0); PG8_MMA(0, 1, At, B1); PG8_BAR; PG8_SCHED;
;             PG8_LDA(At, 0, 1); PG8_STAGE(PG8_SB(0, 0), b2, voffB); PG8_STAGE(PG8_SB(0, 1), b2 + hstep, voffB); PG8_STAGE(PG8_SA(0, 0), a2, voffA);
;             PG8_WAIT_V(8); PG8_WAIT_L(0); PG8_BAR; PG8_MMA(1, 0, At, B0); PG8_MMA(1, 1, At, B1); PG8_BAR; PG8_SCHED;
.LBB0_495:
	ds_read_b128 v[146:149], v164
	ds_read_b128 v[154:157], v164 offset:1024
	ds_read_b128 v[158:161], v164 offset:2048
	ds_read_b128 v[168:171], v164 offset:3072
	ds_read_b128 v[172:175], v165
	ds_read_b128 v[176:179], v165 offset:1024
	ds_read_b128 v[180:183], v165 offset:2048
	ds_read_b128 v[184:187], v165 offset:3072
	s_add_u32 s40, s36, 0xfff80080
	s_addc_u32 s41, s37, -1
	s_cmp_eq_u32 s63, 28
	s_cselect_b32 s43, s5, s41
	s_cselect_b32 s42, s7, s40
	s_cselect_b32 s41, s27, s62
	s_cselect_b32 s40, s29, s61
	v_lshl_add_u64 v[150:151], s[36:37], 0, v[138:139]
	s_add_i32 m0, s45, 0xc000
	ds_read_b128 v[188:191], v166
	ds_read_b128 v[196:199], v166 offset:1024
	ds_read_b128 v[200:203], v166 offset:2048
	ds_read_b128 v[204:207], v166 offset:3072
	ds_read_b128 v[208:211], v166 offset:4096
	ds_read_b128 v[212:215], v166 offset:5120
	ds_read_b128 v[216:219], v166 offset:6144
	ds_read_b128 v[220:223], v166 offset:7168
	global_load_lds_dwordx4 v[150:151], off
	v_lshl_add_u64 v[150:151], s[36:37], 0, v[140:141]
	s_add_i32 m0, s45, 0xe000
	s_nop 0
	global_load_lds_dwordx4 v[150:151], off
	s_waitcnt vmcnt(8)
	s_waitcnt lgkmcnt(0)
	s_barrier
	s_setprio 1
	s_waitcnt lgkmcnt(0)
	v_mfma_f32_16x16x32_bf16 v[124:127], v[146:149], v[188:191], v[124:127]
	v_mfma_f32_16x16x32_bf16 v[120:123], v[158:161], v[188:191], v[120:123]
	v_mfma_f32_16x16x32_bf16 v[108:111], v[146:149], v[200:203], v[108:111]
	v_mfma_f32_16x16x32_bf16 v[104:107], v[158:161], v[200:203], v[104:107]
	v_mfma_f32_16x16x32_bf16 v[92:95], v[146:149], v[208:211], v[92:95]
	v_mfma_f32_16x16x32_bf16 v[88:91], v[158:161], v[208:211], v[88:91]
	v_mfma_f32_16x16x32_bf16 v[76:79], v[146:149], v[216:219], v[76:79]
	v_mfma_f32_16x16x32_bf16 v[72:75], v[158:161], v[216:219], v[72:75]
	v_mfma_f32_16x16x32_bf16 v[124:127], v[154:157], v[196:199], v[124:127]
	v_mfma_f32_16x16x32_bf16 v[120:123], v[168:171], v[196:199], v[120:123]
	v_mfma_f32_16x16x32_bf16 v[108:111], v[154:157], v[204:207], v[108:111]
	v_mfma_f32_16x16x32_bf16 v[104:107], v[168:171], v[204:207], v[104:107]
	v_mfma_f32_16x16x32_bf16 v[92:95], v[154:157], v[212:215], v[92:95]
	v_mfma_f32_16x16x32_bf16 v[88:91], v[168:171], v[212:215], v[88:91]
	v_mfma_f32_16x16x32_bf16 v[76:79], v[154:157], v[220:223], v[76:79]
	v_mfma_f32_16x16x32_bf16 v[72:75], v[168:171], v[220:223], v[72:75]
	v_mfma_f32_16x16x32_bf16 v[116:119], v[172:175], v[188:191], v[116:119]
	v_mfma_f32_16x16x32_bf16 v[112:115], v[180:183], v[188:191], v[112:115]
	v_mfma_f32_16x16x32_bf16 v[100:103], v[172:175], v[200:203], v[100:103]
	v_mfma_f32_16x16x32_bf16 v[96:99], v[180:183], v[200:203], v[96:99]
	v_mfma_f32_16x16x32_bf16 v[84:87], v[172:175], v[208:211], v[84:87]
	v_mfma_f32_16x16x32_bf16 v[80:83], v[180:183], v[208:211], v[80:83]
	v_mfma_f32_16x16x32_bf16 v[68:71], v[172:175], v[216:219], v[68:71]
	v_mfma_f32_16x16x32_bf16 v[64:67], v[180:183], v[216:219], v[64:67]
	v_mfma_f32_16x16x32_bf16 v[116:119], v[176:179], v[196:199], v[116:119]
	v_mfma_f32_16x16x32_bf16 v[112:115], v[184:187], v[196:199], v[112:115]
	v_mfma_f32_16x16x32_bf16 v[100:103], v[176:179], v[204:207], v[100:103]
	v_mfma_f32_16x16x32_bf16 v[96:99], v[184:187], v[204:207], v[96:99]
	v_mfma_f32_16x16x32_bf16 v[84:87], v[176:179], v[212:215], v[84:87]
	v_mfma_f32_16x16x32_bf16 v[80:83], v[184:187], v[212:215], v[80:83]
	v_mfma_f32_16x16x32_bf16 v[68:71], v[176:179], v[220:223], v[68:71]
	v_mfma_f32_16x16x32_bf16 v[64:67], v[184:187], v[220:223], v[64:67]
	s_setprio 0
	s_barrier
	s_add_i32 s64, s55, s44
	v_lshl_add_u64 v[150:151], s[40:41], 0, v[130:131]
	s_mov_b32 m0, s64
	ds_read_b128 v[188:191], v166 offset:16384
	ds_read_b128 v[196:199], v166 offset:17408
	ds_read_b128 v[200:203], v166 offset:18432
	ds_read_b128 v[204:207], v166 offset:19456
	ds_read_b128 v[208:211], v166 offset:20480
	ds_read_b128 v[212:215], v166 offset:21504
	ds_read_b128 v[216:219], v166 offset:22528
	ds_read_b128 v[220:223], v166 offset:23552
	global_load_lds_dwordx4 v[150:151], off
	s_add_i32 m0, s64, 0x2000
	s_add_u32 s64, s40, 0x80000
	v_lshl_add_u64 v[192:193], s[40:41], 0, v[134:135]
	s_addc_u32 s65, s41, 0
	s_add_i32 s66, s56, s44
	global_load_lds_dwordx4 v[192:193], off
	v_lshl_add_u64 v[224:225], s[64:65], 0, v[130:131]
	s_mov_b32 m0, s66
	v_lshl_add_u64 v[226:227], s[42:43], 0, v[132:133]
	global_load_lds_dwordx4 v[224:225], off
	v_lshl_add_u64 v[224:225], s[64:65], 0, v[134:135]
	s_add_i32 m0, s66, 0x2000
	s_nop 0
	global_load_lds_dwordx4 v[224:225], off
	v_lshl_add_u64 v[224:225], s[42:43], 0, v[128:129]
	s_mov_b32 m0, s45
	s_nop 0
	global_load_lds_dwordx4 v[224:225], off
	s_mov_b32 m0, s46
	s_nop 0
	global_load_lds_dwordx4 v[226:227], off
	s_waitcnt vmcnt(8)
	s_waitcnt lgkmcnt(0)
	s_barrier
; #define PG8_STAGE(bufoff, gbase, voff) do { _Pragma("unroll") for (int _i = 0; _i < 2; ++_i) \
;         __builtin_amdgcn_global_load_lds((const unsigned*)((const char*)(gbase) + (voff)[_i]), (PG8_LAS unsigned*)(lds + (bufoff) + ldsw + _i * 8192), 16, 0, 0); } while (0)
; #define PG8_LDA(dst, b, h) do { _Pragma("unroll") for (int m = 0; m < 4; ++m) _Pragma("unroll") for (int k = 0; k < 2; ++k) dst[m][k] = *(const PG8_LAS bf16x8*)(lds + PG8_SA(b, h) + aoff + m * 2048 + k * 1024); } while (0)
; #define PG8_LDB(dst, b, h) do { _Pragma("unroll") for (int n = 0; n < 2; ++n) _Pragma("unroll") for (int k = 0; k < 2; ++k) dst[n][k] = *(const PG8_LAS bf16x8*)(lds + PG8_SB(b, h) + boff + n * 2048 + k * 1024); } while (0)
; #define PG8_MMA(ai, bj, At, Bt) do { __builtin_amdgcn_s_setprio(1); _Pragma("unroll") for (int m = 0; m < 4; ++m) _Pragma("unroll") for (int n = 0; n < 2; ++n) _Pragma("unroll") for (int k = 0; k < 2; ++k) \
;         acc[ai][bj][m][n] = __builtin_amdgcn_mfma_f32_16x16x32_bf16(Bt[n][k], At[m][k], acc[ai][bj][m][n], 0, 0, 0); __builtin_amdgcn_s_setprio(0); } while (0)
; #define PG8_WAIT_V(n) asm volatile("s_waitcnt vmcnt(" #n ")" ::: "memory")
; #define PG8_WAIT_L(n) asm volatile("s_waitcnt lgkmcnt(" #n ")" ::: "memory")
; #define PG8_BAR __builtin_amdgcn_s_barrier()
; #define PG8_SCHED __builtin_amdgcn_sched_barrier(0)
; template <class Epi, class Sched, bool ALIGN_EPI = false, bool SP2 = false>
; __device__ __forceinline__ void gemm_phase(PG8_LAS unsigned char* lds, const Gemm g, const Sched& S, const Epi& E, const int wave_) {
;     ...
;             PG8_WAIT_V(8); PG8_WAIT_L(0); PG8_BAR; PG8_MMA(1, 0, At, B0); PG8_MMA(1, 1, At, B1); PG8_BAR; PG8_SCHED;
;             PG8_LDB(B0, 1, 0); PG8_LDB(B1, 1, 1); PG8_SCHED; PG8_LDA(At, 1, 0); PG8_STAGE(PG8_SA(0, 1), a2 + hstep, voffA);
;             PG8_WAIT_V(8); PG8_WAIT_L(0); PG8_BAR; PG8_MMA(0, 0, At, B0); PG8_MMA(0, 1, At, B1); PG8_BAR; PG8_SCHED;
	s_setprio 1
	s_waitcnt lgkmcnt(0)
	v_mfma_f32_16x16x32_bf16 v[60:63], v[146:149], v[188:191], v[60:63]
	v_mfma_f32_16x16x32_bf16 v[56:59], v[158:161], v[188:191], v[56:59]
	v_mfma_f32_16x16x32_bf16 v[44:47], v[146:149], v[200:203], v[44:47]
	v_mfma_f32_16x16x32_bf16 v[40:43], v[158:161], v[200:203], v[40:43]
	v_mfma_f32_16x16x32_bf16 v[28:31], v[146:149], v[208:211], v[28:31]
	v_mfma_f32_16x16x32_bf16 v[24:27], v[158:161], v[208:211], v[24:27]
	v_mfma_f32_16x16x32_bf16 v[12:15], v[146:149], v[216:219], v[12:15]
	v_mfma_f32_16x16x32_bf16 v[8:11], v[158:161], v[216:219], v[8:11]
	v_mfma_f32_16x16x32_bf16 v[60:63], v[154:157], v[196:199], v[60:63]
	v_mfma_f32_16x16x32_bf16 v[56:59], v[168:171], v[196:199], v[56:59]
	v_mfma_f32_16x16x32_bf16 v[44:47], v[154:157], v[204:207], v[44:47]
	v_mfma_f32_16x16x32_bf16 v[40:43], v[168:171], v[204:207], v[40:43]
	v_mfma_f32_16x16x32_bf16 v[28:31], v[154:157], v[212:215], v[28:31]
	v_mfma_f32_16x16x32_bf16 v[24:27], v[168:171], v[212:215], v[24:27]
	v_mfma_f32_16x16x32_bf16 v[12:15], v[154:157], v[220:223], v[12:15]
	v_mfma_f32_16x16x32_bf16 v[8:11], v[168:171], v[220:223], v[8:11]
	v_mfma_f32_16x16x32_bf16 v[52:55], v[172:175], v[188:191], v[52:55]
	v_mfma_f32_16x16x32_bf16 v[48:51], v[180:183], v[188:191], v[48:51]
	v_mfma_f32_16x16x32_bf16 v[36:39], v[172:175], v[200:203], v[36:39]
	v_mfma_f32_16x16x32_bf16 v[32:35], v[180:183], v[200:203], v[32:35]
	v_mfma_f32_16x16x32_bf16 v[20:23], v[172:175], v[208:211], v[20:23]
	v_mfma_f32_16x16x32_bf16 v[16:19], v[180:183], v[208:211], v[16:19]
	v_mfma_f32_16x16x32_bf16 v[4:7], v[172:175], v[216:219], v[4:7]
	v_mfma_f32_16x16x32_bf16 v[0:3], v[180:183], v[216:219], v[0:3]
	v_mfma_f32_16x16x32_bf16 v[52:55], v[176:179], v[196:199], v[52:55]
	v_mfma_f32_16x16x32_bf16 v[48:51], v[184:187], v[196:199], v[48:51]
	v_mfma_f32_16x16x32_bf16 v[36:39], v[176:179], v[204:207], v[36:39]
	v_mfma_f32_16x16x32_bf16 v[32:35], v[184:187], v[204:207], v[32:35]
	v_mfma_f32_16x16x32_bf16 v[20:23], v[176:179], v[212:215], v[20:23]
	v_mfma_f32_16x16x32_bf16 v[16:19], v[184:187], v[212:215], v[16:19]
	v_mfma_f32_16x16x32_bf16 v[4:7], v[176:179], v[220:223], v[4:7]
	v_mfma_f32_16x16x32_bf16 v[0:3], v[184:187], v[220:223], v[0:3]
	s_setprio 0
	s_barrier
	s_add_i32 s64, 0, 0x18000
	v_add_u32_e32 v136, s64, v162
	s_add_i32 s65, 0, 0x1c000
	ds_read_b128 v[146:149], v136
	ds_read_b128 v[154:157], v136 offset:1024
	ds_read_b128 v[158:161], v136 offset:2048
	ds_read_b128 v[168:171], v136 offset:3072
	v_add_u32_e32 v136, s65, v162
	ds_read_b128 v[172:175], v136
	ds_read_b128 v[176:179], v136 offset:1024
	ds_read_b128 v[180:183], v136 offset:2048
	ds_read_b128 v[184:187], v136 offset:3072
	s_add_u32 s42, s42, 0x80000
	s_addc_u32 s43, s43, 0
	s_mov_b32 m0, s47
	v_lshl_add_u64 v[228:229], s[42:43], 0, v[128:129]
	ds_read_b128 v[188:191], v166 offset:32768
	ds_read_b128 v[196:199], v166 offset:33792
	ds_read_b128 v[200:203], v166 offset:34816
	ds_read_b128 v[204:207], v166 offset:35840
	ds_read_b128 v[208:211], v166 offset:36864
	ds_read_b128 v[212:215], v166 offset:37888
	ds_read_b128 v[216:219], v166 offset:38912
	ds_read_b128 v[220:223], v166 offset:39936
	global_load_lds_dwordx4 v[228:229], off
	v_lshl_add_u64 v[228:229], s[42:43], 0, v[132:133]
	s_mov_b32 m0, s48
	s_nop 0
	global_load_lds_dwordx4 v[228:229], off
	s_waitcnt vmcnt(8)
	s_waitcnt lgkmcnt(0)
	s_barrier
	s_setprio 1
	s_waitcnt lgkmcnt(0)
	v_mfma_f32_16x16x32_bf16 v[124:127], v[146:149], v[188:191], v[124:127]
	v_mfma_f32_16x16x32_bf16 v[120:123], v[158:161], v[188:191], v[120:123]
	v_mfma_f32_16x16x32_bf16 v[108:111], v[146:149], v[200:203], v[108:111]
	v_mfma_f32_16x16x32_bf16 v[104:107], v[158:161], v[200:203], v[104:107]
	v_mfma_f32_16x16x32_bf16 v[92:95], v[146:149], v[208:211], v[92:95]
	v_mfma_f32_16x16x32_bf16 v[88:91], v[158:161], v[208:211], v[88:91]
	v_mfma_f32_16x16x32_bf16 v[76:79], v[146:149], v[216:219], v[76:79]
	v_mfma_f32_16x16x32_bf16 v[72:75], v[158:161], v[216:219], v[72:75]
	v_mfma_f32_16x16x32_bf16 v[124:127], v[154:157], v[196:199], v[124:127]
	v_mfma_f32_16x16x32_bf16 v[120:123], v[168:171], v[196:199], v[120:123]
	v_mfma_f32_16x16x32_bf16 v[108:111], v[154:157], v[204:207], v[108:111]
	v_mfma_f32_16x16x32_bf16 v[104:107], v[168:171], v[204:207], v[104:107]
	v_mfma_f32_16x16x32_bf16 v[92:95], v[154:157], v[212:215], v[92:95]
	v_mfma_f32_16x16x32_bf16 v[88:91], v[168:171], v[212:215], v[88:91]
	v_mfma_f32_16x16x32_bf16 v[76:79], v[154:157], v[220:223], v[76:79]
	v_mfma_f32_16x16x32_bf16 v[72:75], v[168:171], v[220:223], v[72:75]
	v_mfma_f32_16x16x32_bf16 v[116:119], v[172:175], v[188:191], v[116:119]
	v_mfma_f32_16x16x32_bf16 v[112:115], v[180:183], v[188:191], v[112:115]
	v_mfma_f32_16x16x32_bf16 v[100:103], v[172:175], v[200:203], v[100:103]
	v_mfma_f32_16x16x32_bf16 v[96:99], v[180:183], v[200:203], v[96:99]
	v_mfma_f32_16x16x32_bf16 v[84:87], v[172:175], v[208:211], v[84:87]
	v_mfma_f32_16x16x32_bf16 v[80:83], v[180:183], v[208:211], v[80:83]
	v_mfma_f32_16x16x32_bf16 v[68:71], v[172:175], v[216:219], v[68:71]
	v_mfma_f32_16x16x32_bf16 v[64:67], v[180:183], v[216:219], v[64:67]
	v_mfma_f32_16x16x32_bf16 v[116:119], v[176:179], v[196:199], v[116:119]
	v_mfma_f32_16x16x32_bf16 v[112:115], v[184:187], v[196:199], v[112:115]
	v_mfma_f32_16x16x32_bf16 v[100:103], v[176:179], v[204:207], v[100:103]
	v_mfma_f32_16x16x32_bf16 v[96:99], v[184:187], v[204:207], v[96:99]
	v_mfma_f32_16x16x32_bf16 v[84:87], v[176:179], v[212:215], v[84:87]
	v_mfma_f32_16x16x32_bf16 v[80:83], v[184:187], v[212:215], v[80:83]
	v_mfma_f32_16x16x32_bf16 v[68:71], v[176:179], v[220:223], v[68:71]
	v_mfma_f32_16x16x32_bf16 v[64:67], v[184:187], v[220:223], v[64:67]
	s_setprio 0
	s_barrier
; #define PG8_STAGE(bufoff, gbase, voff) do { _Pragma("unroll") for (int _i = 0; _i < 2; ++_i) \
;         __builtin_amdgcn_global_load_lds((const unsigned*)((const char*)(gbase) + (voff)[_i]), (PG8_LAS unsigned*)(lds + (bufoff) + ldsw + _i * 8192), 16, 0, 0); } while (0)
; #define PG8_LDA(dst, b, h) do { _Pragma("unroll") for (int m = 0; m < 4; ++m) _Pragma("unroll") for (int k = 0; k < 2; ++k) dst[m][k] = *(const PG8_LAS bf16x8*)(lds + PG8_SA(b, h) + aoff + m * 2048 + k * 1024); } while (0)
; #define PG8_MMA(ai, bj, At, Bt) do { __builtin_amdgcn_s_setprio(1); _Pragma("unroll") for (int m = 0; m < 4; ++m) _Pragma("unroll") for (int n = 0; n < 2; ++n) _Pragma("unroll") for (int k = 0; k < 2; ++k) \
;         acc[ai][bj][m][n] = __builtin_amdgcn_mfma_f32_16x16x32_bf16(Bt[n][k], At[m][k], acc[ai][bj][m][n], 0, 0, 0); __builtin_amdgcn_s_setprio(0); } while (0)
; #define PG8_WAIT_V(n) asm volatile("s_waitcnt vmcnt(" #n ")" ::: "memory")
; #define PG8_WAIT_L(n) asm volatile("s_waitcnt lgkmcnt(" #n ")" ::: "memory")
; #define PG8_BAR __builtin_amdgcn_s_barrier()
; #define PG8_SCHED __builtin_amdgcn_sched_barrier(0)
; template <class Epi, class Sched, bool ALIGN_EPI = false, bool SP2 = false>
; __device__ __forceinline__ void gemm_phase(PG8_LAS unsigned char* lds, const Gemm g, const Sched& S, const Epi& E, const int wave_) {
;     ...
;         for (int t = 0; t < nt; t += 2) {
;             const bool last = (t == nt - 2);
;             const char* a1 = cA + (size_t)(t + 1) * kstep;
;             const char* a2 = last ? nA : cA + (size_t)(t + 2) * kstep; const char* b2 = last ? nB : cB + (size_t)(t + 2) * kstep;
;             const char* a3 = a2 + kstep; const char* b3 = b2 + kstep;
;     ...
;             PG8_LDA(At, 1, 1); PG8_STAGE(PG8_SB(1, 0), b3, voffB); PG8_STAGE(PG8_SB(1, 1), b3 + hstep, voffB); PG8_STAGE(PG8_SA(1, 0), a3, voffA);
;             PG8_WAIT_V(8); PG8_WAIT_L(0); PG8_BAR; PG8_MMA(1, 0, At, B0); PG8_MMA(1, 1, At, B1); PG8_BAR; PG8_SCHED;
	s_add_i32 s42, s64, s44
	v_lshl_add_u64 v[150:151], v[150:151], 0, s[18:19]
	s_mov_b32 m0, s42
	ds_read_b128 v[188:191], v166 offset:49152
	ds_read_b128 v[196:199], v166 offset:50176
	ds_read_b128 v[200:203], v166 offset:51200
	ds_read_b128 v[204:207], v166 offset:52224
	ds_read_b128 v[208:211], v166 offset:53248
	ds_read_b128 v[212:215], v166 offset:54272
	ds_read_b128 v[216:219], v166 offset:55296
	ds_read_b128 v[220:223], v166 offset:56320
	global_load_lds_dwordx4 v[150:151], off
	s_add_i32 m0, s42, 0x2000
	s_add_u32 s40, s40, 0x80080
	v_lshl_add_u64 v[150:151], v[192:193], 0, s[18:19]
	s_addc_u32 s41, s41, 0
	s_add_i32 s42, s65, s44
	global_load_lds_dwordx4 v[150:151], off
	v_lshl_add_u64 v[150:151], s[40:41], 0, v[130:131]
	s_mov_b32 m0, s42
	s_nop 0
	global_load_lds_dwordx4 v[150:151], off
	v_lshl_add_u64 v[150:151], s[40:41], 0, v[134:135]
	s_add_i32 m0, s42, 0x2000
	s_nop 0
	global_load_lds_dwordx4 v[150:151], off
	v_lshl_add_u64 v[150:151], v[224:225], 0, s[18:19]
	s_mov_b32 m0, s52
	s_nop 0
	global_load_lds_dwordx4 v[150:151], off
	v_lshl_add_u64 v[150:151], v[226:227], 0, s[18:19]
	s_mov_b32 m0, s53
	s_nop 0
	global_load_lds_dwordx4 v[150:151], off
	s_waitcnt vmcnt(8)
	s_waitcnt lgkmcnt(0)
	s_barrier
	s_setprio 1
	s_waitcnt lgkmcnt(0)
	v_mfma_f32_16x16x32_bf16 v[60:63], v[146:149], v[188:191], v[60:63]
	v_mfma_f32_16x16x32_bf16 v[56:59], v[158:161], v[188:191], v[56:59]
	v_mfma_f32_16x16x32_bf16 v[44:47], v[146:149], v[200:203], v[44:47]
	v_mfma_f32_16x16x32_bf16 v[40:43], v[158:161], v[200:203], v[40:43]
	v_mfma_f32_16x16x32_bf16 v[28:31], v[146:149], v[208:211], v[28:31]
	v_mfma_f32_16x16x32_bf16 v[24:27], v[158:161], v[208:211], v[24:27]
	v_mfma_f32_16x16x32_bf16 v[12:15], v[146:149], v[216:219], v[12:15]
	v_mfma_f32_16x16x32_bf16 v[8:11], v[158:161], v[216:219], v[8:11]
	v_mfma_f32_16x16x32_bf16 v[60:63], v[154:157], v[196:199], v[60:63]
	v_mfma_f32_16x16x32_bf16 v[56:59], v[168:171], v[196:199], v[56:59]
	v_mfma_f32_16x16x32_bf16 v[44:47], v[154:157], v[204:207], v[44:47]
	v_mfma_f32_16x16x32_bf16 v[40:43], v[168:171], v[204:207], v[40:43]
	v_mfma_f32_16x16x32_bf16 v[28:31], v[154:157], v[212:215], v[28:31]
	v_mfma_f32_16x16x32_bf16 v[24:27], v[168:171], v[212:215], v[24:27]
	v_mfma_f32_16x16x32_bf16 v[12:15], v[154:157], v[220:223], v[12:15]
	v_mfma_f32_16x16x32_bf16 v[8:11], v[168:171], v[220:223], v[8:11]
	v_mfma_f32_16x16x32_bf16 v[52:55], v[172:175], v[188:191], v[52:55]
	v_mfma_f32_16x16x32_bf16 v[48:51], v[180:183], v[188:191], v[48:51]
	v_mfma_f32_16x16x32_bf16 v[36:39], v[172:175], v[200:203], v[36:39]
	v_mfma_f32_16x16x32_bf16 v[32:35], v[180:183], v[200:203], v[32:35]
	v_mfma_f32_16x16x32_bf16 v[20:23], v[172:175], v[208:211], v[20:23]
	v_mfma_f32_16x16x32_bf16 v[16:19], v[180:183], v[208:211], v[16:19]
	v_mfma_f32_16x16x32_bf16 v[4:7], v[172:175], v[216:219], v[4:7]
	v_mfma_f32_16x16x32_bf16 v[0:3], v[180:183], v[216:219], v[0:3]
	v_mfma_f32_16x16x32_bf16 v[52:55], v[176:179], v[196:199], v[52:55]
	v_mfma_f32_16x16x32_bf16 v[48:51], v[184:187], v[196:199], v[48:51]
	v_mfma_f32_16x16x32_bf16 v[36:39], v[176:179], v[204:207], v[36:39]
	v_mfma_f32_16x16x32_bf16 v[32:35], v[184:187], v[204:207], v[32:35]
	v_mfma_f32_16x16x32_bf16 v[20:23], v[176:179], v[212:215], v[20:23]
	v_mfma_f32_16x16x32_bf16 v[16:19], v[184:187], v[212:215], v[16:19]
	v_mfma_f32_16x16x32_bf16 v[4:7], v[176:179], v[220:223], v[4:7]
	v_mfma_f32_16x16x32_bf16 v[0:3], v[184:187], v[220:223], v[0:3]
	s_setprio 0
	s_barrier
	s_add_i32 s63, s63, 2
	s_add_u32 s36, s36, 0x100
	s_addc_u32 s37, s37, 0
	s_add_u32 s61, s61, 0x100
	s_addc_u32 s62, s62, 0
	s_cmp_gt_u32 s63, 29
	s_cbranch_scc0 .LBB0_495
	s_and_b64 vcc, exec, s[16:17]
	s_cbranch_vccz .LBB0_498
	s_barrier

; #define PG8_STAGE(bufoff, gbase, voff) do { _Pragma("unroll") for (int _i = 0; _i < 2; ++_i) \
;         __builtin_amdgcn_global_load_lds((const unsigned*)((const char*)(gbase) + (voff)[_i]), (PG8_LAS unsigned*)(lds + (bufoff) + ldsw + _i * 8192), 16, 0, 0); } while (0)
; #define PG8_LDA(dst, b, h) do { _Pragma("unroll") for (int m = 0; m < 4; ++m) _Pragma("unroll") for (int k = 0; k < 2; ++k) dst[m][k] = *(const PG8_LAS bf16x8*)(lds + PG8_SA(b, h) + aoff + m * 2048 + k * 1024); } while (0)
; #define PG8_LDB(dst, b, h) do { _Pragma("unroll") for (int n = 0; n < 2; ++n) _Pragma("unroll") for (int k = 0; k < 2; ++k) dst[n][k] = *(const PG8_LAS bf16x8*)(lds + PG8_SB(b, h) + boff + n * 2048 + k * 1024); } while (0)
; #define PG8_MMA(ai, bj, At, Bt) do { __builtin_amdgcn_s_setprio(1); _Pragma("unroll") for (int m = 0; m < 4; ++m) _Pragma("unroll") for (int n = 0; n < 2; ++n) _Pragma("unroll") for (int k = 0; k < 2; ++k) \
;         acc[ai][bj][m][n] = __builtin_amdgcn_mfma_f32_16x16x32_bf16(Bt[n][k], At[m][k], acc[ai][bj][m][n], 0, 0, 0); __builtin_amdgcn_s_setprio(0); } while (0)
; #define PG8_WAIT_V(n) asm volatile("s_waitcnt vmcnt(" #n ")" ::: "memory")
; #define PG8_WAIT_L(n) asm volatile("s_waitcnt lgkmcnt(" #n ")" ::: "memory")
; template <class Epi, class Sched, bool ALIGN_EPI = false, bool SP2 = false>
; __device__ __forceinline__ void gemm_phase(PG8_LAS unsigned char* lds, const Gemm g, const Sched& S, const Epi& E, const int wave_) {
;     ...
;             const bool last = (t == nt - 2);
;             const char* a1 = cA + (size_t)(t + 1) * kstep;
;             const char* a2 = last ? nA : cA + (size_t)(t + 2) * kstep; const char* b2 = last ? nB : cB + (size_t)(t + 2) * kstep;
;             const char* a3 = a2 + kstep; const char* b3 = b2 + kstep;
;             if (last && has_next) S.a_ready(nxt);
;             if constexpr (SP2) {
;             PG8_LDB(B0, 0, 0); PG8_LDB(B1, 0, 1); PG8_SCHED; PG8_LDA(At, 0, 0); PG8_STAGE(PG8_SA(1, 1), a1 + hstep, voffA);
;             PG8_WAIT_V(8); PG8_WAIT_L(0); PG8_BAR; PG8_MMA(0, 0, At, B0); PG8_MMA(0, 1, At, B1); PG8_BAR; PG8_SCHED;
;             PG8_LDA(At, 0, 1); PG8_STAGE(PG8_SB(0, 0), b2, voffB); PG8_STAGE(PG8_SB(0, 1), b2 + hstep, voffB); PG8_STAGE(PG8_SA(0, 0), a2, voffA);
;             PG8_WAIT_V(8); PG8_WAIT_L(0); PG8_BAR; PG8_MMA(1, 0, At, B0); PG8_MMA(1, 1, At, B1); PG8_BAR; PG8_SCHED;
.LBB0_700:
	ds_read_b128 v[128:131], v187
	ds_read_b128 v[132:135], v187 offset:1024
	ds_read_b128 v[136:139], v187 offset:2048
	ds_read_b128 v[140:143], v187 offset:3072
	ds_read_b128 v[160:163], v188
	ds_read_b128 v[164:167], v188 offset:1024
	ds_read_b128 v[168:171], v188 offset:2048
	ds_read_b128 v[172:175], v188 offset:3072
	s_add_u32 s36, s34, 0xfff80080
	s_addc_u32 s37, s35, -1
	s_cmp_eq_u32 s58, 28
	s_cselect_b32 s41, s23, s37
	s_cselect_b32 s40, s29, s36
	s_cselect_b32 s37, s21, s57
	s_cselect_b32 s36, s31, s56
	v_lshl_add_u64 v[180:181], s[34:35], 0, v[152:153]
	s_add_i32 m0, s42, 0xc000
	ds_read_b128 v[176:179], v189
	ds_read_b128 v[196:199], v189 offset:1024
	ds_read_b128 v[200:203], v189 offset:2048
	ds_read_b128 v[204:207], v189 offset:3072
	ds_read_b128 v[208:211], v189 offset:4096
	ds_read_b128 v[212:215], v189 offset:5120
	ds_read_b128 v[216:219], v189 offset:6144
	ds_read_b128 v[220:223], v189 offset:7168
	global_load_lds_dwordx4 v[180:181], off
	v_lshl_add_u64 v[180:181], s[34:35], 0, v[154:155]
	s_add_i32 m0, s42, 0xe000
	s_nop 0
	global_load_lds_dwordx4 v[180:181], off
	s_waitcnt vmcnt(8)
	s_waitcnt lgkmcnt(0)
	s_barrier
	s_setprio 1
	s_waitcnt lgkmcnt(0)
	v_mfma_f32_16x16x32_bf16 v[40:43], v[128:131], v[176:179], v[40:43]
	v_mfma_f32_16x16x32_bf16 v[36:39], v[136:139], v[176:179], v[36:39]
	v_mfma_f32_16x16x32_bf16 v[68:71], v[128:131], v[200:203], v[68:71]
	v_mfma_f32_16x16x32_bf16 v[64:67], v[136:139], v[200:203], v[64:67]
	v_mfma_f32_16x16x32_bf16 v[100:103], v[128:131], v[208:211], v[100:103]
	v_mfma_f32_16x16x32_bf16 v[96:99], v[136:139], v[208:211], v[96:99]
	v_mfma_f32_16x16x32_bf16 v[124:127], v[128:131], v[216:219], v[124:127]
	v_mfma_f32_16x16x32_bf16 v[120:123], v[136:139], v[216:219], v[120:123]
	v_mfma_f32_16x16x32_bf16 v[40:43], v[132:135], v[196:199], v[40:43]
	v_mfma_f32_16x16x32_bf16 v[36:39], v[140:143], v[196:199], v[36:39]
	v_mfma_f32_16x16x32_bf16 v[68:71], v[132:135], v[204:207], v[68:71]
	v_mfma_f32_16x16x32_bf16 v[64:67], v[140:143], v[204:207], v[64:67]
	v_mfma_f32_16x16x32_bf16 v[100:103], v[132:135], v[212:215], v[100:103]
	v_mfma_f32_16x16x32_bf16 v[96:99], v[140:143], v[212:215], v[96:99]
	v_mfma_f32_16x16x32_bf16 v[124:127], v[132:135], v[220:223], v[124:127]
	v_mfma_f32_16x16x32_bf16 v[120:123], v[140:143], v[220:223], v[120:123]
	v_mfma_f32_16x16x32_bf16 v[44:47], v[160:163], v[176:179], v[44:47]
	v_mfma_f32_16x16x32_bf16 v[52:55], v[168:171], v[176:179], v[52:55]
	v_mfma_f32_16x16x32_bf16 v[72:75], v[160:163], v[200:203], v[72:75]
	v_mfma_f32_16x16x32_bf16 v[76:79], v[168:171], v[200:203], v[76:79]
	v_mfma_f32_16x16x32_bf16 v[104:107], v[160:163], v[208:211], v[104:107]
	v_mfma_f32_16x16x32_bf16 v[108:111], v[168:171], v[208:211], v[108:111]
	v_mfma_f32_16x16x32_bf16 v[116:119], v[160:163], v[216:219], v[116:119]
	v_mfma_f32_16x16x32_bf16 v[112:115], v[168:171], v[216:219], v[112:115]
	v_mfma_f32_16x16x32_bf16 v[44:47], v[164:167], v[196:199], v[44:47]
	v_mfma_f32_16x16x32_bf16 v[52:55], v[172:175], v[196:199], v[52:55]
	v_mfma_f32_16x16x32_bf16 v[72:75], v[164:167], v[204:207], v[72:75]
	v_mfma_f32_16x16x32_bf16 v[76:79], v[172:175], v[204:207], v[76:79]
	v_mfma_f32_16x16x32_bf16 v[104:107], v[164:167], v[212:215], v[104:107]
	v_mfma_f32_16x16x32_bf16 v[108:111], v[172:175], v[212:215], v[108:111]
	v_mfma_f32_16x16x32_bf16 v[116:119], v[164:167], v[220:223], v[116:119]
	v_mfma_f32_16x16x32_bf16 v[112:115], v[172:175], v[220:223], v[112:115]
	s_setprio 0
	s_barrier
	s_add_i32 s59, s54, s2
	v_lshl_add_u64 v[180:181], s[36:37], 0, v[146:147]
	s_mov_b32 m0, s59
	ds_read_b128 v[176:179], v189 offset:16384
	ds_read_b128 v[196:199], v189 offset:17408
	ds_read_b128 v[200:203], v189 offset:18432
	ds_read_b128 v[204:207], v189 offset:19456
	ds_read_b128 v[208:211], v189 offset:20480
	ds_read_b128 v[212:215], v189 offset:21504
	ds_read_b128 v[216:219], v189 offset:22528
	ds_read_b128 v[220:223], v189 offset:23552
	global_load_lds_dwordx4 v[180:181], off
	s_add_i32 m0, s59, 0x2000
	s_add_u32 s60, s36, 0x80000
	v_lshl_add_u64 v[192:193], s[36:37], 0, v[150:151]
	s_addc_u32 s61, s37, 0
	s_add_i32 s59, s55, s2
	global_load_lds_dwordx4 v[192:193], off
	v_lshl_add_u64 v[224:225], s[60:61], 0, v[146:147]
	s_mov_b32 m0, s59
	v_lshl_add_u64 v[226:227], s[40:41], 0, v[148:149]
	global_load_lds_dwordx4 v[224:225], off
	v_lshl_add_u64 v[224:225], s[60:61], 0, v[150:151]
	s_add_i32 m0, s59, 0x2000
	s_nop 0
	global_load_lds_dwordx4 v[224:225], off
	v_lshl_add_u64 v[224:225], s[40:41], 0, v[144:145]
	s_mov_b32 m0, s42
	s_nop 0
	global_load_lds_dwordx4 v[224:225], off
	s_mov_b32 m0, s43
	s_nop 0
	global_load_lds_dwordx4 v[226:227], off
	s_waitcnt vmcnt(8)
	s_waitcnt lgkmcnt(0)
	s_barrier
; #define PG8_STAGE(bufoff, gbase, voff) do { _Pragma("unroll") for (int _i = 0; _i < 2; ++_i) \
;         __builtin_amdgcn_global_load_lds((const unsigned*)((const char*)(gbase) + (voff)[_i]), (PG8_LAS unsigned*)(lds + (bufoff) + ldsw + _i * 8192), 16, 0, 0); } while (0)
; #define PG8_LDA(dst, b, h) do { _Pragma("unroll") for (int m = 0; m < 4; ++m) _Pragma("unroll") for (int k = 0; k < 2; ++k) dst[m][k] = *(const PG8_LAS bf16x8*)(lds + PG8_SA(b, h) + aoff + m * 2048 + k * 1024); } while (0)
; #define PG8_LDB(dst, b, h) do { _Pragma("unroll") for (int n = 0; n < 2; ++n) _Pragma("unroll") for (int k = 0; k < 2; ++k) dst[n][k] = *(const PG8_LAS bf16x8*)(lds + PG8_SB(b, h) + boff + n * 2048 + k * 1024); } while (0)
; #define PG8_MMA(ai, bj, At, Bt) do { __builtin_amdgcn_s_setprio(1); _Pragma("unroll") for (int m = 0; m < 4; ++m) _Pragma("unroll") for (int n = 0; n < 2; ++n) _Pragma("unroll") for (int k = 0; k < 2; ++k) \
;         acc[ai][bj][m][n] = __builtin_amdgcn_mfma_f32_16x16x32_bf16(Bt[n][k], At[m][k], acc[ai][bj][m][n], 0, 0, 0); __builtin_amdgcn_s_setprio(0); } while (0)
; #define PG8_WAIT_V(n) asm volatile("s_waitcnt vmcnt(" #n ")" ::: "memory")
; #define PG8_WAIT_L(n) asm volatile("s_waitcnt lgkmcnt(" #n ")" ::: "memory")
; #define PG8_BAR __builtin_amdgcn_s_barrier()
; #define PG8_SCHED __builtin_amdgcn_sched_barrier(0)
; template <class Epi, class Sched, bool ALIGN_EPI = false, bool SP2 = false>
; __device__ __forceinline__ void gemm_phase(PG8_LAS unsigned char* lds, const Gemm g, const Sched& S, const Epi& E, const int wave_) {
;     ...
;             PG8_WAIT_V(8); PG8_WAIT_L(0); PG8_BAR; PG8_MMA(1, 0, At, B0); PG8_MMA(1, 1, At, B1); PG8_BAR; PG8_SCHED;
;             PG8_LDB(B0, 1, 0); PG8_LDB(B1, 1, 1); PG8_SCHED; PG8_LDA(At, 1, 0); PG8_STAGE(PG8_SA(0, 1), a2 + hstep, voffA);
;             PG8_WAIT_V(8); PG8_WAIT_L(0); PG8_BAR; PG8_MMA(0, 0, At, B0); PG8_MMA(0, 1, At, B1); PG8_BAR; PG8_SCHED;
	s_setprio 1
	s_waitcnt lgkmcnt(0)
	v_mfma_f32_16x16x32_bf16 v[92:95], v[128:131], v[176:179], v[92:95]
	v_mfma_f32_16x16x32_bf16 v[88:91], v[136:139], v[176:179], v[88:91]
	v_mfma_f32_16x16x32_bf16 v[60:63], v[128:131], v[200:203], v[60:63]
	v_mfma_f32_16x16x32_bf16 v[56:59], v[136:139], v[200:203], v[56:59]
	v_mfma_f32_16x16x32_bf16 v[28:31], v[128:131], v[208:211], v[28:31]
	v_mfma_f32_16x16x32_bf16 v[24:27], v[136:139], v[208:211], v[24:27]
	v_mfma_f32_16x16x32_bf16 v[12:15], v[128:131], v[216:219], v[12:15]
	v_mfma_f32_16x16x32_bf16 v[8:11], v[136:139], v[216:219], v[8:11]
	v_mfma_f32_16x16x32_bf16 v[92:95], v[132:135], v[196:199], v[92:95]
	v_mfma_f32_16x16x32_bf16 v[88:91], v[140:143], v[196:199], v[88:91]
	v_mfma_f32_16x16x32_bf16 v[60:63], v[132:135], v[204:207], v[60:63]
	v_mfma_f32_16x16x32_bf16 v[56:59], v[140:143], v[204:207], v[56:59]
	v_mfma_f32_16x16x32_bf16 v[28:31], v[132:135], v[212:215], v[28:31]
	v_mfma_f32_16x16x32_bf16 v[24:27], v[140:143], v[212:215], v[24:27]
	v_mfma_f32_16x16x32_bf16 v[12:15], v[132:135], v[220:223], v[12:15]
	v_mfma_f32_16x16x32_bf16 v[8:11], v[140:143], v[220:223], v[8:11]
	v_mfma_f32_16x16x32_bf16 v[84:87], v[160:163], v[176:179], v[84:87]
	v_mfma_f32_16x16x32_bf16 v[80:83], v[168:171], v[176:179], v[80:83]
	v_mfma_f32_16x16x32_bf16 v[48:51], v[160:163], v[200:203], v[48:51]
	v_mfma_f32_16x16x32_bf16 v[32:35], v[168:171], v[200:203], v[32:35]
	v_mfma_f32_16x16x32_bf16 v[20:23], v[160:163], v[208:211], v[20:23]
	v_mfma_f32_16x16x32_bf16 v[16:19], v[168:171], v[208:211], v[16:19]
	v_mfma_f32_16x16x32_bf16 v[4:7], v[160:163], v[216:219], v[4:7]
	v_mfma_f32_16x16x32_bf16 v[0:3], v[168:171], v[216:219], v[0:3]
	v_mfma_f32_16x16x32_bf16 v[84:87], v[164:167], v[196:199], v[84:87]
	v_mfma_f32_16x16x32_bf16 v[80:83], v[172:175], v[196:199], v[80:83]
	v_mfma_f32_16x16x32_bf16 v[48:51], v[164:167], v[204:207], v[48:51]
	v_mfma_f32_16x16x32_bf16 v[32:35], v[172:175], v[204:207], v[32:35]
	v_mfma_f32_16x16x32_bf16 v[20:23], v[164:167], v[212:215], v[20:23]
	v_mfma_f32_16x16x32_bf16 v[16:19], v[172:175], v[212:215], v[16:19]
	v_mfma_f32_16x16x32_bf16 v[4:7], v[164:167], v[220:223], v[4:7]
	v_mfma_f32_16x16x32_bf16 v[0:3], v[172:175], v[220:223], v[0:3]
	s_setprio 0
	s_barrier
	s_add_i32 s59, 0, 0x18000
	s_add_i32 s60, 0, 0x1c000
	v_add_u32_e32 v140, s59, v183
	v_add_u32_e32 v172, s60, v183
	ds_read_b128 v[128:131], v140
	ds_read_b128 v[132:135], v140 offset:1024
	ds_read_b128 v[136:139], v140 offset:2048
	ds_read_b128 v[140:143], v140 offset:3072
	ds_read_b128 v[160:163], v172
	ds_read_b128 v[164:167], v172 offset:1024
	ds_read_b128 v[168:171], v172 offset:2048
	ds_read_b128 v[172:175], v172 offset:3072
	s_add_u32 s40, s40, 0x80000
	s_addc_u32 s41, s41, 0
	s_mov_b32 m0, s44
	v_lshl_add_u64 v[228:229], s[40:41], 0, v[144:145]
	ds_read_b128 v[176:179], v189 offset:32768
	ds_read_b128 v[196:199], v189 offset:33792
	ds_read_b128 v[200:203], v189 offset:34816
	ds_read_b128 v[204:207], v189 offset:35840
	ds_read_b128 v[208:211], v189 offset:36864
	ds_read_b128 v[212:215], v189 offset:37888
	ds_read_b128 v[216:219], v189 offset:38912
	ds_read_b128 v[220:223], v189 offset:39936
	global_load_lds_dwordx4 v[228:229], off
	v_lshl_add_u64 v[228:229], s[40:41], 0, v[148:149]
	s_mov_b32 m0, s45
	s_nop 0
	global_load_lds_dwordx4 v[228:229], off
	s_waitcnt vmcnt(8)
	s_waitcnt lgkmcnt(0)
	s_barrier
	s_setprio 1
	s_waitcnt lgkmcnt(0)
	v_mfma_f32_16x16x32_bf16 v[40:43], v[128:131], v[176:179], v[40:43]
	v_mfma_f32_16x16x32_bf16 v[36:39], v[136:139], v[176:179], v[36:39]
	v_mfma_f32_16x16x32_bf16 v[68:71], v[128:131], v[200:203], v[68:71]
	v_mfma_f32_16x16x32_bf16 v[64:67], v[136:139], v[200:203], v[64:67]
	v_mfma_f32_16x16x32_bf16 v[100:103], v[128:131], v[208:211], v[100:103]
	v_mfma_f32_16x16x32_bf16 v[96:99], v[136:139], v[208:211], v[96:99]
	v_mfma_f32_16x16x32_bf16 v[124:127], v[128:131], v[216:219], v[124:127]
	v_mfma_f32_16x16x32_bf16 v[120:123], v[136:139], v[216:219], v[120:123]
	v_mfma_f32_16x16x32_bf16 v[40:43], v[132:135], v[196:199], v[40:43]
	v_mfma_f32_16x16x32_bf16 v[36:39], v[140:143], v[196:199], v[36:39]
	v_mfma_f32_16x16x32_bf16 v[68:71], v[132:135], v[204:207], v[68:71]
	v_mfma_f32_16x16x32_bf16 v[64:67], v[140:143], v[204:207], v[64:67]
	v_mfma_f32_16x16x32_bf16 v[100:103], v[132:135], v[212:215], v[100:103]
	v_mfma_f32_16x16x32_bf16 v[96:99], v[140:143], v[212:215], v[96:99]
	v_mfma_f32_16x16x32_bf16 v[124:127], v[132:135], v[220:223], v[124:127]
	v_mfma_f32_16x16x32_bf16 v[120:123], v[140:143], v[220:223], v[120:123]
	v_mfma_f32_16x16x32_bf16 v[44:47], v[160:163], v[176:179], v[44:47]
	v_mfma_f32_16x16x32_bf16 v[52:55], v[168:171], v[176:179], v[52:55]
	v_mfma_f32_16x16x32_bf16 v[72:75], v[160:163], v[200:203], v[72:75]
	v_mfma_f32_16x16x32_bf16 v[76:79], v[168:171], v[200:203], v[76:79]
	v_mfma_f32_16x16x32_bf16 v[104:107], v[160:163], v[208:211], v[104:107]
	v_mfma_f32_16x16x32_bf16 v[108:111], v[168:171], v[208:211], v[108:111]
	v_mfma_f32_16x16x32_bf16 v[116:119], v[160:163], v[216:219], v[116:119]
	v_mfma_f32_16x16x32_bf16 v[112:115], v[168:171], v[216:219], v[112:115]
	v_mfma_f32_16x16x32_bf16 v[44:47], v[164:167], v[196:199], v[44:47]
	v_mfma_f32_16x16x32_bf16 v[52:55], v[172:175], v[196:199], v[52:55]
	v_mfma_f32_16x16x32_bf16 v[72:75], v[164:167], v[204:207], v[72:75]
	v_mfma_f32_16x16x32_bf16 v[76:79], v[172:175], v[204:207], v[76:79]
	v_mfma_f32_16x16x32_bf16 v[104:107], v[164:167], v[212:215], v[104:107]
	v_mfma_f32_16x16x32_bf16 v[108:111], v[172:175], v[212:215], v[108:111]
	v_mfma_f32_16x16x32_bf16 v[116:119], v[164:167], v[220:223], v[116:119]
	v_mfma_f32_16x16x32_bf16 v[112:115], v[172:175], v[220:223], v[112:115]
	s_setprio 0
	s_barrier
; #define PG8_STAGE(bufoff, gbase, voff) do { _Pragma("unroll") for (int _i = 0; _i < 2; ++_i) \
;         __builtin_amdgcn_global_load_lds((const unsigned*)((const char*)(gbase) + (voff)[_i]), (PG8_LAS unsigned*)(lds + (bufoff) + ldsw + _i * 8192), 16, 0, 0); } while (0)
; #define PG8_LDA(dst, b, h) do { _Pragma("unroll") for (int m = 0; m < 4; ++m) _Pragma("unroll") for (int k = 0; k < 2; ++k) dst[m][k] = *(const PG8_LAS bf16x8*)(lds + PG8_SA(b, h) + aoff + m * 2048 + k * 1024); } while (0)
; #define PG8_MMA(ai, bj, At, Bt) do { __builtin_amdgcn_s_setprio(1); _Pragma("unroll") for (int m = 0; m < 4; ++m) _Pragma("unroll") for (int n = 0; n < 2; ++n) _Pragma("unroll") for (int k = 0; k < 2; ++k) \
;         acc[ai][bj][m][n] = __builtin_amdgcn_mfma_f32_16x16x32_bf16(Bt[n][k], At[m][k], acc[ai][bj][m][n], 0, 0, 0); __builtin_amdgcn_s_setprio(0); } while (0)
; #define PG8_WAIT_V(n) asm volatile("s_waitcnt vmcnt(" #n ")" ::: "memory")
; #define PG8_WAIT_L(n) asm volatile("s_waitcnt lgkmcnt(" #n ")" ::: "memory")
; #define PG8_BAR __builtin_amdgcn_s_barrier()
; #define PG8_SCHED __builtin_amdgcn_sched_barrier(0)
; template <class Epi, class Sched, bool ALIGN_EPI = false, bool SP2 = false>
; __device__ __forceinline__ void gemm_phase(PG8_LAS unsigned char* lds, const Gemm g, const Sched& S, const Epi& E, const int wave_) {
;     ...
;         for (int t = 0; t < nt; t += 2) {
;             const bool last = (t == nt - 2);
;             const char* a1 = cA + (size_t)(t + 1) * kstep;
;             const char* a2 = last ? nA : cA + (size_t)(t + 2) * kstep; const char* b2 = last ? nB : cB + (size_t)(t + 2) * kstep;
;             const char* a3 = a2 + kstep; const char* b3 = b2 + kstep;
;     ...
;             PG8_LDA(At, 1, 1); PG8_STAGE(PG8_SB(1, 0), b3, voffB); PG8_STAGE(PG8_SB(1, 1), b3 + hstep, voffB); PG8_STAGE(PG8_SA(1, 0), a3, voffA);
;             PG8_WAIT_V(8); PG8_WAIT_L(0); PG8_BAR; PG8_MMA(1, 0, At, B0); PG8_MMA(1, 1, At, B1); PG8_BAR; PG8_SCHED;
	s_add_i32 s40, s59, s2
	v_lshl_add_u64 v[180:181], v[180:181], 0, s[18:19]
	s_mov_b32 m0, s40
	ds_read_b128 v[176:179], v189 offset:49152
	ds_read_b128 v[196:199], v189 offset:50176
	ds_read_b128 v[200:203], v189 offset:51200
	ds_read_b128 v[204:207], v189 offset:52224
	ds_read_b128 v[208:211], v189 offset:53248
	ds_read_b128 v[212:215], v189 offset:54272
	ds_read_b128 v[216:219], v189 offset:55296
	ds_read_b128 v[220:223], v189 offset:56320
	global_load_lds_dwordx4 v[180:181], off
	s_add_i32 m0, s40, 0x2000
	s_add_u32 s36, s36, 0x80080
	v_lshl_add_u64 v[180:181], v[192:193], 0, s[18:19]
	s_addc_u32 s37, s37, 0
	s_add_i32 s40, s60, s2
	global_load_lds_dwordx4 v[180:181], off
	v_lshl_add_u64 v[180:181], s[36:37], 0, v[146:147]
	s_mov_b32 m0, s40
	s_nop 0
	global_load_lds_dwordx4 v[180:181], off
	v_lshl_add_u64 v[180:181], s[36:37], 0, v[150:151]
	s_add_i32 m0, s40, 0x2000
	s_nop 0
	global_load_lds_dwordx4 v[180:181], off
	v_lshl_add_u64 v[180:181], v[224:225], 0, s[18:19]
	s_mov_b32 m0, s51
	s_nop 0
	global_load_lds_dwordx4 v[180:181], off
	v_lshl_add_u64 v[180:181], v[226:227], 0, s[18:19]
	s_mov_b32 m0, s52
	s_nop 0
	global_load_lds_dwordx4 v[180:181], off
	s_waitcnt vmcnt(8)
	s_waitcnt lgkmcnt(0)
	s_barrier
	s_setprio 1
	s_waitcnt lgkmcnt(0)
	v_mfma_f32_16x16x32_bf16 v[92:95], v[128:131], v[176:179], v[92:95]
	v_mfma_f32_16x16x32_bf16 v[88:91], v[136:139], v[176:179], v[88:91]
	v_mfma_f32_16x16x32_bf16 v[60:63], v[128:131], v[200:203], v[60:63]
	v_mfma_f32_16x16x32_bf16 v[56:59], v[136:139], v[200:203], v[56:59]
	v_mfma_f32_16x16x32_bf16 v[28:31], v[128:131], v[208:211], v[28:31]
	v_mfma_f32_16x16x32_bf16 v[24:27], v[136:139], v[208:211], v[24:27]
	v_mfma_f32_16x16x32_bf16 v[12:15], v[128:131], v[216:219], v[12:15]
	v_mfma_f32_16x16x32_bf16 v[8:11], v[136:139], v[216:219], v[8:11]
	v_mfma_f32_16x16x32_bf16 v[92:95], v[132:135], v[196:199], v[92:95]
	v_mfma_f32_16x16x32_bf16 v[88:91], v[140:143], v[196:199], v[88:91]
	v_mfma_f32_16x16x32_bf16 v[60:63], v[132:135], v[204:207], v[60:63]
	v_mfma_f32_16x16x32_bf16 v[56:59], v[140:143], v[204:207], v[56:59]
	v_mfma_f32_16x16x32_bf16 v[28:31], v[132:135], v[212:215], v[28:31]
	v_mfma_f32_16x16x32_bf16 v[24:27], v[140:143], v[212:215], v[24:27]
	v_mfma_f32_16x16x32_bf16 v[12:15], v[132:135], v[220:223], v[12:15]
	v_mfma_f32_16x16x32_bf16 v[8:11], v[140:143], v[220:223], v[8:11]
	v_mfma_f32_16x16x32_bf16 v[84:87], v[160:163], v[176:179], v[84:87]
	v_mfma_f32_16x16x32_bf16 v[80:83], v[168:171], v[176:179], v[80:83]
	v_mfma_f32_16x16x32_bf16 v[48:51], v[160:163], v[200:203], v[48:51]
	v_mfma_f32_16x16x32_bf16 v[32:35], v[168:171], v[200:203], v[32:35]
	v_mfma_f32_16x16x32_bf16 v[20:23], v[160:163], v[208:211], v[20:23]
	v_mfma_f32_16x16x32_bf16 v[16:19], v[168:171], v[208:211], v[16:19]
	v_mfma_f32_16x16x32_bf16 v[4:7], v[160:163], v[216:219], v[4:7]
	v_mfma_f32_16x16x32_bf16 v[0:3], v[168:171], v[216:219], v[0:3]
	v_mfma_f32_16x16x32_bf16 v[84:87], v[164:167], v[196:199], v[84:87]
	v_mfma_f32_16x16x32_bf16 v[80:83], v[172:175], v[196:199], v[80:83]
	v_mfma_f32_16x16x32_bf16 v[48:51], v[164:167], v[204:207], v[48:51]
	v_mfma_f32_16x16x32_bf16 v[32:35], v[172:175], v[204:207], v[32:35]
	v_mfma_f32_16x16x32_bf16 v[20:23], v[164:167], v[212:215], v[20:23]
	v_mfma_f32_16x16x32_bf16 v[16:19], v[172:175], v[212:215], v[16:19]
	v_mfma_f32_16x16x32_bf16 v[4:7], v[164:167], v[220:223], v[4:7]
	v_mfma_f32_16x16x32_bf16 v[0:3], v[172:175], v[220:223], v[0:3]
	s_setprio 0
	s_barrier
	s_add_i32 s58, s58, 2
	s_add_u32 s34, s34, 0x100
	s_addc_u32 s35, s35, 0
	s_add_u32 s56, s56, 0x100
	s_addc_u32 s57, s57, 0
	s_cmp_gt_u32 s58, 29
	s_cbranch_scc0 .LBB0_700
	s_and_b64 vcc, exec, s[14:15]
	s_cbranch_vccz .LBB0_703
	s_barrier
